# attention steady loops: the four exact no-op '0 + x' row-sum adds removed; rest as v72
# speedup vs baseline: 1.0117x; 1.0001x over previous
; #define WAIT_BAR(N) asm volatile("s_waitcnt vmcnt(" #N ") lgkmcnt(0)\n\ts_barrier":::"memory")
;   #define RESC() do{ if(!FIXREF&&resc){ asm volatile("s_waitcnt lgkmcnt(0)":::"memory"); \
;       _Pragma("unroll") for(int d_=0;d_<2;++d_) _Pragma("unroll") for(int r=0;r<16;++r)o[d_][r]*=wsf[crow(r,hi)]; } }while(0)
;   #define ROT() do{sl_prev=sl_cur;sl_cur=sl_next;sl_next=(sl_next==(NSLOT-1)*SLOTB)?0:sl_next+SLOTB;}while(0)
; template<int THRL,bool FIXREF,bool HALFK> __device__ __forceinline__ void attn_unit(float mref,long rowbase,int q0,const bf16*Qh,int PQ,const bf16*__restrict__ Kh_,int PK,const bf16*__restrict__ Vh_,int PV,bf16*Oh,int PO,const bf16*Gh,int PG,u32x4(&okeep)[4],int omode,float lam,float oml,const float ...
;     ...
;   for(;t+5<NT;t+=2){
;     STEP(pB0,pB1,pA0,pA1,t,true,true,true);     WAIT_BAR(2); RESC(); ROT();
;     STEP(pA0,pA1,pB0,pB1,t+1,true,true,true);   WAIT_BAR(2); RESC(); ROT();
.LBB0_451:
	v_add_u32_e32 v0, s66, v227
	ds_read_b64_tr_b16 v[234:235], v0 offset:24576
	ds_read_b64_tr_b16 v[236:237], v0 offset:25088
	v_add_f32_e32 v102, v82, v83
	v_add_f32_e32 v102, v84, v102
	v_add_f32_e32 v102, v85, v102
	v_add_f32_e32 v102, v86, v102
	v_add_f32_e32 v102, v87, v102
	v_cvt_pk_bf16_f32 v166, v82, v83
	v_cvt_pk_bf16_f32 v167, v84, v85
	s_waitcnt lgkmcnt(9)
	v_mfma_f32_32x32x16_bf16 v[114:129], v[98:101], v[174:177], v[50:65]
	ds_read_b64_tr_b16 v[82:83], v0 offset:28672
	ds_read_b64_tr_b16 v[84:85], v0 offset:29184
	v_add_f32_e32 v98, v88, v102
	v_add_f32_e32 v98, v89, v98
	v_add_f32_e32 v98, v90, v98
	v_add_f32_e32 v146, v91, v98
	s_waitcnt lgkmcnt(10)
	v_mfma_f32_32x32x16_bf16 v[98:113], v[182:185], v[174:177], v[50:65]
	v_cvt_pk_bf16_f32 v168, v86, v87
	v_cvt_pk_bf16_f32 v169, v88, v89
	ds_read_b64_tr_b16 v[86:87], v0 offset:25600
	ds_read_b64_tr_b16 v[88:89], v0 offset:26112
	v_add_f32_e32 v146, v92, v146
	v_add_f32_e32 v146, v93, v146
	v_add_f32_e32 v146, v94, v146
	v_add_f32_e32 v146, v95, v146
	v_cvt_pk_bf16_f32 v158, v90, v91
	v_cvt_pk_bf16_f32 v159, v92, v93
	s_waitcnt lgkmcnt(11)
	v_mfma_f32_32x32x16_bf16 v[114:129], v[186:189], v[170:173], v[114:129]
	ds_read_b64_tr_b16 v[90:91], v0 offset:29696
	ds_read_b64_tr_b16 v[92:93], v0 offset:30208
	s_waitcnt lgkmcnt(12)
	v_mfma_f32_32x32x16_bf16 v[98:113], v[178:181], v[170:173], v[98:113]
	v_add_f32_e32 v146, v96, v146
	v_add_f32_e32 v146, v97, v146
	v_add_f32_e32 v146, v66, v146
	v_add_f32_e32 v146, v67, v146
	v_cvt_pk_bf16_f32 v160, v94, v95
	v_cvt_pk_bf16_f32 v161, v96, v97
	ds_read_b64_tr_b16 v[94:95], v0 offset:26624
	ds_read_b64_tr_b16 v[96:97], v0 offset:27136
	s_waitcnt lgkmcnt(13)
	v_mfma_f32_32x32x16_bf16 v[114:129], v[142:145], v[162:165], v[114:129]
	v_add_f32_e32 v142, v68, v146
	v_add_f32_e32 v142, v69, v142
	v_add_f32_e32 v142, v70, v142
	v_add_f32_e32 v142, v71, v142
	v_cvt_pk_bf16_f32 v150, v66, v67
	v_cvt_pk_bf16_f32 v151, v68, v69
	ds_read_b64_tr_b16 v[66:67], v0 offset:30720
	ds_read_b64_tr_b16 v[68:69], v0 offset:31232
	s_waitcnt lgkmcnt(14)
	v_mfma_f32_32x32x16_bf16 v[98:113], v[138:141], v[162:165], v[98:113]
	v_add_f32_e32 v138, v72, v142
	v_add_f32_e32 v138, v73, v138
	v_add_f32_e32 v138, v74, v138
	v_add_f32_e32 v138, v75, v138
	v_cvt_pk_bf16_f32 v152, v70, v71
	v_cvt_pk_bf16_f32 v153, v72, v73
	ds_read_b64_tr_b16 v[70:71], v0 offset:27648
	ds_read_b64_tr_b16 v[72:73], v0 offset:28160
	s_waitcnt lgkmcnt(14)
	v_mfma_f32_32x32x16_bf16 v[114:129], v[134:137], v[154:157], v[114:129]
	v_add_f32_e32 v134, v76, v138
	v_add_f32_e32 v134, v77, v134
	v_add_f32_e32 v134, v78, v134
	v_add_f32_e32 v134, v79, v134
	v_cvt_pk_bf16_f32 v146, v74, v75
	v_cvt_pk_bf16_f32 v147, v76, v77
	ds_read_b64_tr_b16 v[74:75], v0 offset:31744
	ds_read_b64_tr_b16 v[76:77], v0 offset:32256
	v_mfma_f32_32x32x16_bf16 v[98:113], v[130:133], v[154:157], v[98:113]
	v_add_f32_e32 v0, v80, v134
	v_add_f32_e32 v0, v81, v0
	v_cvt_pk_bf16_f32 v148, v78, v79
	v_cvt_pk_bf16_f32 v149, v80, v81
	v_lshl_add_u64 v[78:79], v[214:215], 0, s[12:13]
	s_add_i32 s40, s65, s62
	s_mov_b32 s41, m0
	s_mov_b32 m0, s40
	s_nop 0
	global_load_lds_dwordx4 v[78:79], off
	s_mov_b32 m0, s41
	v_lshl_add_u64 v[78:79], v[212:213], 0, s[22:23]
	s_add_i32 s40, s49, s61
	s_mov_b32 s41, m0
	s_mov_b32 m0, s40
	s_nop 0
	global_load_lds_dwordx4 v[78:79], off
	s_mov_b32 m0, s41
	v_add_f32_e32 v0, v232, v0
	s_waitcnt lgkmcnt(14)
	v_mfma_f32_32x32x16_bf16 v[18:33], v[166:169], v[234:237], v[18:33]
	v_exp_f32_e32 v114, v114
	v_exp_f32_e32 v115, v115
	v_exp_f32_e32 v116, v116
	v_exp_f32_e32 v117, v117
	s_waitcnt lgkmcnt(12)
	v_mfma_f32_32x32x16_bf16 v[34:49], v[166:169], v[82:85], v[34:49]
	v_exp_f32_e32 v118, v118
	v_exp_f32_e32 v119, v119
	v_exp_f32_e32 v120, v120
	v_exp_f32_e32 v121, v121
	v_add_u32_e32 v82, s49, v228
	ds_read_b128 v[78:81], v82
	ds_read_b128 v[134:137], v82 offset:512
	s_waitcnt lgkmcnt(12)
	v_mfma_f32_32x32x16_bf16 v[18:33], v[158:161], v[86:89], v[18:33]
	v_exp_f32_e32 v122, v122
	v_exp_f32_e32 v123, v123
	v_exp_f32_e32 v124, v124
	v_exp_f32_e32 v125, v125
	ds_read_b128 v[138:141], v82 offset:2048
	ds_read_b128 v[142:145], v82 offset:2560
	s_waitcnt lgkmcnt(12)
	v_mfma_f32_32x32x16_bf16 v[34:49], v[158:161], v[90:93], v[34:49]
	v_exp_f32_e32 v126, v126
	v_exp_f32_e32 v127, v127
	v_exp_f32_e32 v128, v128
	v_exp_f32_e32 v129, v129
	ds_read_b128 v[178:181], v82 offset:4096
	ds_read_b128 v[182:185], v82 offset:4608
	s_waitcnt lgkmcnt(12)
	v_mfma_f32_32x32x16_bf16 v[18:33], v[150:153], v[94:97], v[18:33]
	v_exp_f32_e32 v98, v98
	v_exp_f32_e32 v99, v99
	v_exp_f32_e32 v100, v100
	v_exp_f32_e32 v101, v101
	ds_read_b128 v[186:189], v82 offset:6144
	ds_read_b128 v[130:133], v82 offset:6656
	s_waitcnt lgkmcnt(12)
	v_mfma_f32_32x32x16_bf16 v[34:49], v[150:153], v[66:69], v[34:49]
	v_exp_f32_e32 v102, v102
	v_exp_f32_e32 v103, v103
	v_exp_f32_e32 v104, v104
	v_exp_f32_e32 v105, v105
	s_waitcnt lgkmcnt(10)
	v_mfma_f32_32x32x16_bf16 v[18:33], v[146:149], v[70:73], v[18:33]
	v_exp_f32_e32 v106, v106
	v_exp_f32_e32 v107, v107
	v_exp_f32_e32 v108, v108
	v_exp_f32_e32 v109, v109
	s_waitcnt lgkmcnt(8)
	v_mfma_f32_32x32x16_bf16 v[34:49], v[146:149], v[74:77], v[34:49]
	v_exp_f32_e32 v110, v110
	v_exp_f32_e32 v111, v111
	v_exp_f32_e32 v112, v112
	v_exp_f32_e32 v113, v113
	s_add_i32 s40, s49, 0x2000
	s_cmpk_lg_i32 s49, 0x4000
	s_cselect_b32 s40, s40, 0
	v_add_u32_e32 v232, s65, v227
	s_waitcnt vmcnt(2) lgkmcnt(0)
	s_barrier
; #define WAIT_BAR(N) asm volatile("s_waitcnt vmcnt(" #N ") lgkmcnt(0)\n\ts_barrier":::"memory")
;   #define RESC() do{ if(!FIXREF&&resc){ asm volatile("s_waitcnt lgkmcnt(0)":::"memory"); \
;       _Pragma("unroll") for(int d_=0;d_<2;++d_) _Pragma("unroll") for(int r=0;r<16;++r)o[d_][r]*=wsf[crow(r,hi)]; } }while(0)
;   #define ROT() do{sl_prev=sl_cur;sl_cur=sl_next;sl_next=(sl_next==(NSLOT-1)*SLOTB)?0:sl_next+SLOTB;}while(0)
; template<int THRL,bool FIXREF,bool HALFK> __device__ __forceinline__ void attn_unit(float mref,long rowbase,int q0,const bf16*Qh,int PQ,const bf16*__restrict__ Kh_,int PK,const bf16*__restrict__ Vh_,int PV,bf16*Oh,int PO,const bf16*Gh,int PG,u32x4(&okeep)[4],int omode,float lam,float oml,const float ...
;     ...
;   for(;t+5<NT;t+=2){
;     STEP(pB0,pB1,pA0,pA1,t,true,true,true);     WAIT_BAR(2); RESC(); ROT();
;     STEP(pA0,pA1,pB0,pB1,t+1,true,true,true);   WAIT_BAR(2); RESC(); ROT();
	ds_read_b64_tr_b16 v[234:235], v232 offset:24576
	ds_read_b64_tr_b16 v[236:237], v232 offset:25088
	s_waitcnt lgkmcnt(9)
	v_mfma_f32_32x32x16_bf16 v[82:97], v[78:81], v[174:177], v[50:65]
	v_add_f32_e32 v66, v114, v115
	v_add_f32_e32 v66, v116, v66
	v_add_f32_e32 v66, v117, v66
	v_add_f32_e32 v66, v118, v66
	v_add_f32_e32 v66, v119, v66
	v_cvt_pk_bf16_f32 v166, v114, v115
	v_cvt_pk_bf16_f32 v167, v116, v117
	ds_read_b64_tr_b16 v[114:115], v232 offset:28672
	ds_read_b64_tr_b16 v[116:117], v232 offset:29184
	v_add_f32_e32 v66, v120, v66
	v_add_f32_e32 v66, v121, v66
	v_add_f32_e32 v66, v122, v66
	v_add_f32_e32 v146, v123, v66
	s_waitcnt lgkmcnt(10)
	v_mfma_f32_32x32x16_bf16 v[66:81], v[134:137], v[174:177], v[50:65]
	v_cvt_pk_bf16_f32 v168, v118, v119
	v_cvt_pk_bf16_f32 v169, v120, v121
	ds_read_b64_tr_b16 v[118:119], v232 offset:25600
	ds_read_b64_tr_b16 v[120:121], v232 offset:26112
	s_waitcnt lgkmcnt(11)
	v_mfma_f32_32x32x16_bf16 v[82:97], v[138:141], v[170:173], v[82:97]
	v_add_f32_e32 v134, v124, v146
	v_add_f32_e32 v134, v125, v134
	v_add_f32_e32 v134, v126, v134
	v_add_f32_e32 v134, v127, v134
	v_cvt_pk_bf16_f32 v158, v122, v123
	v_cvt_pk_bf16_f32 v159, v124, v125
	ds_read_b64_tr_b16 v[122:123], v232 offset:29696
	ds_read_b64_tr_b16 v[124:125], v232 offset:30208
	s_waitcnt lgkmcnt(12)
	v_mfma_f32_32x32x16_bf16 v[66:81], v[142:145], v[170:173], v[66:81]
	v_add_f32_e32 v134, v128, v134
	v_add_f32_e32 v134, v129, v134
	v_add_f32_e32 v134, v98, v134
	v_add_f32_e32 v134, v99, v134
	v_cvt_pk_bf16_f32 v160, v126, v127
	v_cvt_pk_bf16_f32 v161, v128, v129
	ds_read_b64_tr_b16 v[126:127], v232 offset:26624
	ds_read_b64_tr_b16 v[128:129], v232 offset:27136
	s_waitcnt lgkmcnt(13)
	v_mfma_f32_32x32x16_bf16 v[82:97], v[178:181], v[162:165], v[82:97]
	v_add_f32_e32 v134, v100, v134
	v_add_f32_e32 v134, v101, v134
	v_add_f32_e32 v134, v102, v134
	v_add_f32_e32 v134, v103, v134
	v_cvt_pk_bf16_f32 v150, v98, v99
	v_cvt_pk_bf16_f32 v151, v100, v101
	ds_read_b64_tr_b16 v[238:239], v232 offset:30720
	ds_read_b64_tr_b16 v[240:241], v232 offset:31232
	s_waitcnt lgkmcnt(14)
	v_mfma_f32_32x32x16_bf16 v[66:81], v[182:185], v[162:165], v[66:81]
	v_add_f32_e32 v98, v104, v134
	v_add_f32_e32 v98, v105, v98
	v_add_f32_e32 v98, v106, v98
	v_add_f32_e32 v98, v107, v98
	v_cvt_pk_bf16_f32 v152, v102, v103
	v_cvt_pk_bf16_f32 v153, v104, v105
	ds_read_b64_tr_b16 v[102:103], v232 offset:27648
	ds_read_b64_tr_b16 v[104:105], v232 offset:28160
	s_waitcnt lgkmcnt(14)
	v_mfma_f32_32x32x16_bf16 v[82:97], v[186:189], v[154:157], v[82:97]
	v_add_f32_e32 v98, v108, v98
	v_add_f32_e32 v98, v109, v98
	v_add_f32_e32 v98, v110, v98
	v_add_f32_e32 v98, v111, v98
	v_cvt_pk_bf16_f32 v146, v106, v107
	v_cvt_pk_bf16_f32 v147, v108, v109
	ds_read_b64_tr_b16 v[106:107], v232 offset:31744
	ds_read_b64_tr_b16 v[108:109], v232 offset:32256
	v_mfma_f32_32x32x16_bf16 v[66:81], v[130:133], v[154:157], v[66:81]
	v_add_f32_e32 v98, v112, v98
	v_add_f32_e32 v98, v113, v98
	v_cvt_pk_bf16_f32 v148, v110, v111
	v_cvt_pk_bf16_f32 v149, v112, v113
	s_nop 0
	v_add_f32_e32 v232, v0, v98
	v_lshl_add_u64 v[98:99], v[214:215], 0, s[92:93]
	s_add_i32 s41, s49, s62
	s_mov_b32 s42, m0
	s_mov_b32 m0, s41
	s_nop 0
	global_load_lds_dwordx4 v[98:99], off
	s_mov_b32 m0, s42
	v_lshl_add_u64 v[212:213], v[212:213], 0, s[4:5]
	s_add_i32 s41, s40, s61
	s_mov_b32 s42, m0
	s_mov_b32 m0, s41
	s_nop 0
	global_load_lds_dwordx4 v[212:213], off
	s_mov_b32 m0, s42
	s_waitcnt lgkmcnt(14)
	v_mfma_f32_32x32x16_bf16 v[18:33], v[166:169], v[234:237], v[18:33]
	v_exp_f32_e32 v82, v82
	v_exp_f32_e32 v83, v83
	v_exp_f32_e32 v84, v84
	v_exp_f32_e32 v85, v85
	s_waitcnt lgkmcnt(12)
	v_mfma_f32_32x32x16_bf16 v[34:49], v[166:169], v[114:117], v[34:49]
	v_exp_f32_e32 v86, v86
	v_exp_f32_e32 v87, v87
	v_exp_f32_e32 v88, v88
	v_exp_f32_e32 v89, v89
	v_add_u32_e32 v0, s40, v228
	ds_read_b128 v[98:101], v0
	ds_read_b128 v[182:185], v0 offset:512
	s_waitcnt lgkmcnt(12)
	v_mfma_f32_32x32x16_bf16 v[18:33], v[158:161], v[118:121], v[18:33]
	v_exp_f32_e32 v90, v90
	v_exp_f32_e32 v91, v91
	v_exp_f32_e32 v92, v92
	v_exp_f32_e32 v93, v93
	ds_read_b128 v[186:189], v0 offset:2048
	ds_read_b128 v[178:181], v0 offset:2560
	s_waitcnt lgkmcnt(12)
	v_mfma_f32_32x32x16_bf16 v[34:49], v[158:161], v[122:125], v[34:49]
	v_exp_f32_e32 v94, v94
	v_exp_f32_e32 v95, v95
	v_exp_f32_e32 v96, v96
	v_exp_f32_e32 v97, v97
	ds_read_b128 v[142:145], v0 offset:4096
	ds_read_b128 v[138:141], v0 offset:4608
	s_waitcnt lgkmcnt(12)
	v_mfma_f32_32x32x16_bf16 v[18:33], v[150:153], v[126:129], v[18:33]
	v_exp_f32_e32 v66, v66
	v_exp_f32_e32 v67, v67
	v_exp_f32_e32 v68, v68
	v_exp_f32_e32 v69, v69
	ds_read_b128 v[134:137], v0 offset:6144
	ds_read_b128 v[130:133], v0 offset:6656
	s_waitcnt lgkmcnt(12)
	v_mfma_f32_32x32x16_bf16 v[34:49], v[150:153], v[238:241], v[34:49]
	v_exp_f32_e32 v70, v70
	v_exp_f32_e32 v71, v71
	v_exp_f32_e32 v72, v72
	v_exp_f32_e32 v73, v73
	s_waitcnt lgkmcnt(10)
	v_mfma_f32_32x32x16_bf16 v[18:33], v[146:149], v[102:105], v[18:33]
	v_exp_f32_e32 v74, v74
	v_exp_f32_e32 v75, v75
	v_exp_f32_e32 v76, v76
	v_exp_f32_e32 v77, v77
	s_waitcnt lgkmcnt(8)
	v_mfma_f32_32x32x16_bf16 v[34:49], v[146:149], v[106:109], v[34:49]
	v_exp_f32_e32 v78, v78
	v_exp_f32_e32 v79, v79
	v_exp_f32_e32 v80, v80
	v_exp_f32_e32 v81, v81
	s_add_i32 s41, s40, 0x2000
	s_cmpk_lg_i32 s40, 0x4000
	s_mov_b32 s66, s49
	s_cselect_b32 s49, s41, 0
	s_add_i32 s48, s48, 2
	v_lshl_add_u64 v[214:215], v[214:215], 0, s[10:11]
	s_mov_b32 s65, s40
	s_cmp_gt_u32 s48, 56
	s_waitcnt vmcnt(2) lgkmcnt(0)
	s_barrier
	s_cbranch_scc0 .LBB0_451
;   #define RESC() do{ if(!FIXREF&&resc){ asm volatile("s_waitcnt lgkmcnt(0)":::"memory"); \
;       _Pragma("unroll") for(int d_=0;d_<2;++d_) _Pragma("unroll") for(int r=0;r<16;++r)o[d_][r]*=wsf[crow(r,hi)]; } }while(0)
;   #define ROT() do{sl_prev=sl_cur;sl_cur=sl_next;sl_next=(sl_next==(NSLOT-1)*SLOTB)?0:sl_next+SLOTB;}while(0)
;   #define ENDW(tt) do{ if((tt)+3<NT){WAIT_BAR(2);} else if((tt)+2<NT){WAIT_BAR(1);} else {WAIT_BAR(0);} }while(0)
; template<int THRL,bool FIXREF,bool HALFK> __device__ __forceinline__ void attn_unit(float mref,long rowbase,int q0,const bf16*Qh,int PQ,const bf16*__restrict__ Kh_,int PK,const bf16*__restrict__ Vh_,int PV,bf16*Oh,int PO,const bf16*Gh,int PG,u32x4(&okeep)[4],int omode,float lam,float oml,const float ...
;     ...
;   for(;t+1<NT;t+=2){
;     STEP(pB0,pB1,pA0,pA1,t,(t+3<NT),(t+1<NT),(t+1<NT));       ENDW(t);   RESC(); ROT();
;     STEP(pA0,pA1,pB0,pB1,t+1,(t+4<NT),(t+2<NT),(t+2<NT));     ENDW(t+1); RESC(); ROT();
	s_and_b32 s41, s64, 0x3fffffc0
	s_cmp_lg_u32 0, -1
	s_cselect_b32 s40, 0, 0
	s_add_i32 s42, s40, 0x6000
	v_add_u32_e32 v0, s42, v231
	s_lshl_b32 s41, s41, 2
	s_add_i32 s42, s41, 0
	v_add3_u32 v0, v0, v229, v230
	ds_read_b64_tr_b16 v[212:213], v227 offset:32768
	ds_read_b64_tr_b16 v[214:215], v227 offset:33280
	v_add_f32_e32 v102, v82, v83
	v_add_f32_e32 v102, v84, v102
	v_add_f32_e32 v102, v85, v102
	v_add_f32_e32 v102, v86, v102
	v_add_f32_e32 v102, v87, v102
	v_cvt_pk_bf16_f32 v166, v82, v83
	v_cvt_pk_bf16_f32 v167, v84, v85
	s_waitcnt lgkmcnt(9)
	v_mfma_f32_32x32x16_bf16 v[114:129], v[98:101], v[174:177], v[50:65]
	ds_read_b64_tr_b16 v[82:83], v227 offset:36864
	ds_read_b64_tr_b16 v[84:85], v227 offset:37376
	v_add_f32_e32 v98, v88, v102
	v_add_f32_e32 v98, v89, v98
	v_add_f32_e32 v98, v90, v98
	v_add_f32_e32 v146, v91, v98
	v_cvt_pk_bf16_f32 v168, v86, v87
	v_cvt_pk_bf16_f32 v169, v88, v89
	s_waitcnt lgkmcnt(10)
	v_mfma_f32_32x32x16_bf16 v[98:113], v[182:185], v[174:177], v[50:65]
	ds_read_b64_tr_b16 v[86:87], v227 offset:33792
	ds_read_b64_tr_b16 v[88:89], v227 offset:34304
	v_add_f32_e32 v146, v92, v146
	v_add_f32_e32 v146, v93, v146
	v_add_f32_e32 v146, v94, v146
	v_add_f32_e32 v146, v95, v146
	v_cvt_pk_bf16_f32 v158, v90, v91
	v_cvt_pk_bf16_f32 v159, v92, v93
	s_waitcnt lgkmcnt(11)
	v_mfma_f32_32x32x16_bf16 v[114:129], v[186:189], v[170:173], v[114:129]
	ds_read_b64_tr_b16 v[90:91], v227 offset:37888
	ds_read_b64_tr_b16 v[92:93], v227 offset:38400
	v_add_f32_e32 v146, v96, v146
	v_add_f32_e32 v146, v97, v146
	v_add_f32_e32 v146, v66, v146
	v_add_f32_e32 v146, v67, v146
	v_cvt_pk_bf16_f32 v160, v94, v95
	v_cvt_pk_bf16_f32 v161, v96, v97
	s_waitcnt lgkmcnt(12)
	v_mfma_f32_32x32x16_bf16 v[98:113], v[178:181], v[170:173], v[98:113]
	ds_read_b64_tr_b16 v[94:95], v227 offset:34816
	ds_read_b64_tr_b16 v[96:97], v227 offset:35328
	s_waitcnt lgkmcnt(13)
	v_mfma_f32_32x32x16_bf16 v[114:129], v[142:145], v[162:165], v[114:129]
	v_add_f32_e32 v142, v68, v146
	v_add_f32_e32 v142, v69, v142
	v_add_f32_e32 v142, v70, v142
	v_add_f32_e32 v142, v71, v142
	v_cvt_pk_bf16_f32 v150, v66, v67
	v_cvt_pk_bf16_f32 v151, v68, v69
	ds_read_b64_tr_b16 v[66:67], v227 offset:38912
	ds_read_b64_tr_b16 v[68:69], v227 offset:39424
	s_waitcnt lgkmcnt(14)
	v_mfma_f32_32x32x16_bf16 v[98:113], v[138:141], v[162:165], v[98:113]
	v_add_f32_e32 v138, v72, v142
	v_add_f32_e32 v138, v73, v138
	v_add_f32_e32 v138, v74, v138
	v_add_f32_e32 v138, v75, v138
	v_cvt_pk_bf16_f32 v152, v70, v71
	v_cvt_pk_bf16_f32 v153, v72, v73
	ds_read_b64_tr_b16 v[70:71], v227 offset:35840
	ds_read_b64_tr_b16 v[72:73], v227 offset:36352
	s_waitcnt lgkmcnt(14)
	v_mfma_f32_32x32x16_bf16 v[114:129], v[134:137], v[154:157], v[114:129]
	v_add_f32_e32 v134, v76, v138
	v_add_f32_e32 v134, v77, v134
	v_add_f32_e32 v134, v78, v134
	v_add_f32_e32 v134, v79, v134
	v_cvt_pk_bf16_f32 v146, v74, v75
	v_cvt_pk_bf16_f32 v147, v76, v77
	ds_read_b64_tr_b16 v[74:75], v227 offset:39936
	ds_read_b64_tr_b16 v[76:77], v227 offset:40448
	v_mfma_f32_32x32x16_bf16 v[98:113], v[130:133], v[154:157], v[98:113]
	v_add_f32_e32 v130, v80, v134
	v_add_f32_e32 v130, v81, v130
	v_add_f32_e32 v130, 0, v130
	v_cvt_pk_bf16_f32 v148, v78, v79
	v_cvt_pk_bf16_f32 v149, v80, v81
	s_mov_b64 s[46:47], 0xf8000
	s_add_i32 s40, s40, s63
	v_lshl_add_u64 v[78:79], v[210:211], 0, s[46:47]
	s_add_i32 s41, s40, 0x4000
	s_mov_b32 s43, m0
	s_mov_b32 m0, s41
	s_nop 0
	global_load_lds_dwordx4 v[78:79], off
	s_mov_b32 m0, s43
	v_lshl_add_u64 v[78:79], v[208:209], 0, s[18:19]
	s_mov_b32 s41, m0
	s_mov_b32 m0, s61
	s_nop 0
	global_load_lds_dwordx4 v[78:79], off
	s_mov_b32 m0, s41
	v_add_f32_e32 v229, v232, v130
	s_waitcnt lgkmcnt(14)
	v_mfma_f32_32x32x16_bf16 v[18:33], v[166:169], v[212:215], v[18:33]
	v_exp_f32_e32 v114, v114
	v_exp_f32_e32 v115, v115
	v_exp_f32_e32 v116, v116
	v_exp_f32_e32 v117, v117
	s_waitcnt lgkmcnt(12)
	v_mfma_f32_32x32x16_bf16 v[34:49], v[166:169], v[82:85], v[34:49]
	v_exp_f32_e32 v118, v118
	v_exp_f32_e32 v119, v119
	v_exp_f32_e32 v120, v120
	v_exp_f32_e32 v121, v121
	ds_read_b128 v[78:81], v228
	ds_read_b128 v[178:181], v228 offset:512
	s_waitcnt lgkmcnt(12)
	v_mfma_f32_32x32x16_bf16 v[18:33], v[158:161], v[86:89], v[18:33]
	v_exp_f32_e32 v122, v122
	v_exp_f32_e32 v123, v123
	v_exp_f32_e32 v124, v124
	v_exp_f32_e32 v125, v125
	ds_read_b128 v[86:89], v228 offset:2048
	ds_read_b128 v[182:185], v228 offset:2560
	s_waitcnt lgkmcnt(12)
	v_mfma_f32_32x32x16_bf16 v[34:49], v[158:161], v[90:93], v[34:49]
	v_exp_f32_e32 v126, v126
	v_exp_f32_e32 v127, v127
	v_exp_f32_e32 v128, v128
	v_exp_f32_e32 v129, v129
	ds_read_b128 v[90:93], v228 offset:4096
	ds_read_b128 v[186:189], v228 offset:4608
	s_waitcnt lgkmcnt(12)
	v_mfma_f32_32x32x16_bf16 v[18:33], v[150:153], v[94:97], v[18:33]
	v_exp_f32_e32 v98, v98
	v_exp_f32_e32 v99, v99
	v_exp_f32_e32 v100, v100
	v_exp_f32_e32 v101, v101
	ds_read_b128 v[94:97], v228 offset:6144
	ds_read_b128 v[82:85], v228 offset:6656
	s_waitcnt lgkmcnt(12)
	v_mfma_f32_32x32x16_bf16 v[34:49], v[150:153], v[66:69], v[34:49]
	v_exp_f32_e32 v102, v102
	v_exp_f32_e32 v103, v103
	v_exp_f32_e32 v104, v104
	v_exp_f32_e32 v105, v105
	s_waitcnt lgkmcnt(10)
	v_mfma_f32_32x32x16_bf16 v[18:33], v[146:149], v[70:73], v[18:33]
	v_exp_f32_e32 v106, v106
	v_exp_f32_e32 v107, v107
	v_exp_f32_e32 v108, v108
	v_exp_f32_e32 v109, v109
	s_waitcnt lgkmcnt(8)
	v_mfma_f32_32x32x16_bf16 v[34:49], v[146:149], v[74:77], v[34:49]
	v_exp_f32_e32 v110, v110
	v_exp_f32_e32 v111, v111
	v_exp_f32_e32 v112, v112
	v_exp_f32_e32 v113, v113
	s_waitcnt vmcnt(2) lgkmcnt(0)
	s_barrier
;   #define RESC() do{ if(!FIXREF&&resc){ asm volatile("s_waitcnt lgkmcnt(0)":::"memory"); \
;       _Pragma("unroll") for(int d_=0;d_<2;++d_) _Pragma("unroll") for(int r=0;r<16;++r)o[d_][r]*=wsf[crow(r,hi)]; } }while(0)
;   #define ROT() do{sl_prev=sl_cur;sl_cur=sl_next;sl_next=(sl_next==(NSLOT-1)*SLOTB)?0:sl_next+SLOTB;}while(0)
;   #define ENDW(tt) do{ if((tt)+3<NT){WAIT_BAR(2);} else if((tt)+2<NT){WAIT_BAR(1);} else {WAIT_BAR(0);} }while(0)
; template<int THRL,bool FIXREF,bool HALFK> __device__ __forceinline__ void attn_unit(float mref,long rowbase,int q0,const bf16*Qh,int PQ,const bf16*__restrict__ Kh_,int PK,const bf16*__restrict__ Vh_,int PV,bf16*Oh,int PO,const bf16*Gh,int PG,u32x4(&okeep)[4],int omode,float lam,float oml,const float ...
;     ...
;   for(;t+1<NT;t+=2){
;     STEP(pB0,pB1,pA0,pA1,t,(t+3<NT),(t+1<NT),(t+1<NT));       ENDW(t);   RESC(); ROT();
;     STEP(pA0,pA1,pB0,pB1,t+1,(t+4<NT),(t+2<NT),(t+2<NT));     ENDW(t+1); RESC(); ROT();
	ds_read_b64_tr_b16 v[212:213], v227 offset:40960
	ds_read_b64_tr_b16 v[214:215], v227 offset:41472
	v_add_f32_e32 v66, v114, v115
	v_add_f32_e32 v66, v116, v66
	v_add_f32_e32 v66, v117, v66
	v_add_f32_e32 v66, v118, v66
	v_add_f32_e32 v66, v119, v66
	v_cvt_pk_bf16_f32 v166, v114, v115
	v_cvt_pk_bf16_f32 v167, v116, v117
	s_waitcnt lgkmcnt(9)
	v_mfma_f32_32x32x16_bf16 v[130:145], v[78:81], v[174:177], v[50:65]
	ds_read_b64_tr_b16 v[114:115], v227 offset:45056
	ds_read_b64_tr_b16 v[116:117], v227 offset:45568
	v_add_f32_e32 v66, v120, v66
	v_add_f32_e32 v66, v121, v66
	v_add_f32_e32 v66, v122, v66
	v_add_f32_e32 v146, v123, v66
	s_waitcnt lgkmcnt(10)
	v_mfma_f32_32x32x16_bf16 v[66:81], v[178:181], v[174:177], v[50:65]
	v_cvt_pk_bf16_f32 v168, v118, v119
	v_cvt_pk_bf16_f32 v169, v120, v121
	ds_read_b64_tr_b16 v[118:119], v227 offset:41984
	ds_read_b64_tr_b16 v[120:121], v227 offset:42496
	s_waitcnt lgkmcnt(11)
	v_mfma_f32_32x32x16_bf16 v[130:145], v[86:89], v[170:173], v[130:145]
	v_add_f32_e32 v86, v124, v146
	v_add_f32_e32 v86, v125, v86
	v_add_f32_e32 v86, v126, v86
	v_add_f32_e32 v146, v127, v86
	v_cvt_pk_bf16_f32 v158, v122, v123
	v_cvt_pk_bf16_f32 v159, v124, v125
	ds_read_b64_tr_b16 v[86:87], v227 offset:46080
	ds_read_b64_tr_b16 v[88:89], v227 offset:46592
	s_waitcnt lgkmcnt(12)
	v_mfma_f32_32x32x16_bf16 v[66:81], v[182:185], v[170:173], v[66:81]
	v_add_f32_e32 v122, v128, v146
	v_add_f32_e32 v122, v129, v122
	v_add_f32_e32 v122, v98, v122
	v_add_f32_e32 v146, v99, v122
	v_cvt_pk_bf16_f32 v160, v126, v127
	v_cvt_pk_bf16_f32 v161, v128, v129
	ds_read_b64_tr_b16 v[122:123], v227 offset:43008
	ds_read_b64_tr_b16 v[124:125], v227 offset:43520
	s_waitcnt lgkmcnt(13)
	v_mfma_f32_32x32x16_bf16 v[130:145], v[90:93], v[162:165], v[130:145]
	v_add_f32_e32 v90, v100, v146
	v_add_f32_e32 v90, v101, v90
	v_add_f32_e32 v90, v102, v90
	v_add_f32_e32 v126, v103, v90
	v_cvt_pk_bf16_f32 v150, v98, v99
	v_cvt_pk_bf16_f32 v151, v100, v101
	ds_read_b64_tr_b16 v[90:91], v227 offset:47104
	ds_read_b64_tr_b16 v[92:93], v227 offset:47616
	s_waitcnt lgkmcnt(14)
	v_mfma_f32_32x32x16_bf16 v[66:81], v[186:189], v[162:165], v[66:81]
	v_add_f32_e32 v98, v104, v126
	v_add_f32_e32 v98, v105, v98
	v_add_f32_e32 v98, v106, v98
	v_add_f32_e32 v98, v107, v98
	v_cvt_pk_bf16_f32 v152, v102, v103
	v_cvt_pk_bf16_f32 v153, v104, v105
	ds_read_b64_tr_b16 v[102:103], v227 offset:44032
	ds_read_b64_tr_b16 v[104:105], v227 offset:44544
	s_waitcnt lgkmcnt(14)
	v_mfma_f32_32x32x16_bf16 v[130:145], v[94:97], v[154:157], v[130:145]
	v_add_f32_e32 v94, v108, v98
	v_add_f32_e32 v94, v109, v94
	v_add_f32_e32 v94, v110, v94
	v_add_f32_e32 v98, v111, v94
	v_cvt_pk_bf16_f32 v146, v106, v107
	v_cvt_pk_bf16_f32 v147, v108, v109
	ds_read_b64_tr_b16 v[94:95], v227 offset:48128
	ds_read_b64_tr_b16 v[96:97], v227 offset:48640
	v_mfma_f32_32x32x16_bf16 v[66:81], v[82:85], v[154:157], v[66:81]
	v_add_f32_e32 v82, v112, v98
	v_add_f32_e32 v82, v113, v82
	v_add_f32_e32 v82, 0, v82
	v_cvt_pk_bf16_f32 v148, v110, v111
	v_cvt_pk_bf16_f32 v149, v112, v113
	s_mov_b64 s[46:47], 0xfc000
	v_add_f32_e32 v229, v229, v82
	v_lshl_add_u64 v[82:83], v[210:211], 0, s[46:47]
	s_mov_b32 s41, m0
	s_mov_b32 m0, s62
	s_nop 0
	global_load_lds_dwordx4 v[82:83], off
	s_mov_b32 m0, s41
	v_lshl_add_u64 v[82:83], v[208:209], 0, s[6:7]
	s_add_i32 s41, s40, 0x8000
	s_mov_b32 s43, m0
	s_mov_b32 m0, s41
	s_nop 0
	global_load_lds_dwordx4 v[82:83], off
	s_mov_b32 m0, s43
	s_waitcnt lgkmcnt(14)
	v_mfma_f32_32x32x16_bf16 v[18:33], v[166:169], v[212:215], v[18:33]
	v_exp_f32_e32 v130, v130
	v_exp_f32_e32 v131, v131
	v_exp_f32_e32 v132, v132
	v_exp_f32_e32 v133, v133
	s_waitcnt lgkmcnt(12)
	v_mfma_f32_32x32x16_bf16 v[34:49], v[166:169], v[114:117], v[34:49]
	v_exp_f32_e32 v134, v134
	v_exp_f32_e32 v135, v135
	v_exp_f32_e32 v136, v136
	v_exp_f32_e32 v137, v137
	ds_read_b128 v[82:85], v228 offset:8192
	ds_read_b128 v[106:109], v228 offset:8704
	s_waitcnt lgkmcnt(12)
	v_mfma_f32_32x32x16_bf16 v[18:33], v[158:161], v[118:121], v[18:33]
	v_exp_f32_e32 v138, v138
	v_exp_f32_e32 v139, v139
	v_exp_f32_e32 v140, v140
	v_exp_f32_e32 v141, v141
	ds_read_b128 v[110:113], v228 offset:10240
	ds_read_b128 v[178:181], v228 offset:10752
	s_waitcnt lgkmcnt(12)
	v_mfma_f32_32x32x16_bf16 v[34:49], v[158:161], v[86:89], v[34:49]
	v_exp_f32_e32 v142, v142
	v_exp_f32_e32 v143, v143
	v_exp_f32_e32 v144, v144
	v_exp_f32_e32 v145, v145
	ds_read_b128 v[182:185], v228 offset:12288
	ds_read_b128 v[186:189], v228 offset:12800
	s_waitcnt lgkmcnt(12)
	v_mfma_f32_32x32x16_bf16 v[18:33], v[150:153], v[122:125], v[18:33]
	v_exp_f32_e32 v66, v66
	v_exp_f32_e32 v67, v67
	v_exp_f32_e32 v68, v68
	v_exp_f32_e32 v69, v69
	ds_read_b128 v[210:213], v228 offset:14336
	ds_read_b128 v[98:101], v228 offset:14848
	s_waitcnt lgkmcnt(12)
	v_mfma_f32_32x32x16_bf16 v[34:49], v[150:153], v[90:93], v[34:49]
	v_exp_f32_e32 v70, v70
	v_exp_f32_e32 v71, v71
	v_exp_f32_e32 v72, v72
	v_exp_f32_e32 v73, v73
	s_waitcnt lgkmcnt(10)
	v_mfma_f32_32x32x16_bf16 v[18:33], v[146:149], v[102:105], v[18:33]
	v_exp_f32_e32 v74, v74
	v_exp_f32_e32 v75, v75
	v_exp_f32_e32 v76, v76
	v_exp_f32_e32 v77, v77
	s_waitcnt lgkmcnt(8)
	v_mfma_f32_32x32x16_bf16 v[34:49], v[146:149], v[94:97], v[34:49]
	v_exp_f32_e32 v78, v78
	v_exp_f32_e32 v79, v79
	v_exp_f32_e32 v80, v80
	v_exp_f32_e32 v81, v81
	s_waitcnt vmcnt(2) lgkmcnt(0)
	s_barrier
;   #define RESC() do{ if(!FIXREF&&resc){ asm volatile("s_waitcnt lgkmcnt(0)":::"memory"); \
;       _Pragma("unroll") for(int d_=0;d_<2;++d_) _Pragma("unroll") for(int r=0;r<16;++r)o[d_][r]*=wsf[crow(r,hi)]; } }while(0)
;   #define ROT() do{sl_prev=sl_cur;sl_cur=sl_next;sl_next=(sl_next==(NSLOT-1)*SLOTB)?0:sl_next+SLOTB;}while(0)
;   #define ENDW(tt) do{ if((tt)+3<NT){WAIT_BAR(2);} else if((tt)+2<NT){WAIT_BAR(1);} else {WAIT_BAR(0);} }while(0)
; template<int THRL,bool FIXREF,bool HALFK> __device__ __forceinline__ void attn_unit(float mref,long rowbase,int q0,const bf16*Qh,int PQ,const bf16*__restrict__ Kh_,int PK,const bf16*__restrict__ Vh_,int PV,bf16*Oh,int PO,const bf16*Gh,int PG,u32x4(&okeep)[4],int omode,float lam,float oml,const float ...
;     ...
;   for(;t+1<NT;t+=2){
;     STEP(pB0,pB1,pA0,pA1,t,(t+3<NT),(t+1<NT),(t+1<NT));       ENDW(t);   RESC(); ROT();
;     STEP(pA0,pA1,pB0,pB1,t+1,(t+4<NT),(t+2<NT),(t+2<NT));     ENDW(t+1); RESC(); ROT();
	ds_read_b64_tr_b16 v[102:103], v227 offset:24576
	ds_read_b64_tr_b16 v[104:105], v227 offset:25088
	v_add_f32_e32 v86, v130, v131
	v_add_f32_e32 v86, v132, v86
	v_add_f32_e32 v86, v133, v86
	v_add_f32_e32 v86, v134, v86
	v_add_f32_e32 v86, v135, v86
	v_cvt_pk_bf16_f32 v166, v130, v131
	v_cvt_pk_bf16_f32 v167, v132, v133
	s_waitcnt lgkmcnt(9)
	v_mfma_f32_32x32x16_bf16 v[114:129], v[82:85], v[174:177], v[50:65]
	ds_read_b64_tr_b16 v[130:131], v227 offset:28672
	ds_read_b64_tr_b16 v[132:133], v227 offset:29184
	v_add_f32_e32 v82, v136, v86
	v_add_f32_e32 v82, v137, v82
	v_add_f32_e32 v82, v138, v82
	v_add_f32_e32 v146, v139, v82
	v_cvt_pk_bf16_f32 v168, v134, v135
	v_cvt_pk_bf16_f32 v169, v136, v137
	s_waitcnt lgkmcnt(10)
	v_mfma_f32_32x32x16_bf16 v[82:97], v[106:109], v[174:177], v[50:65]
	ds_read_b64_tr_b16 v[106:107], v227 offset:25600
	ds_read_b64_tr_b16 v[108:109], v227 offset:26112
	s_waitcnt lgkmcnt(11)
	v_mfma_f32_32x32x16_bf16 v[114:129], v[110:113], v[170:173], v[114:129]
	v_add_f32_e32 v110, v140, v146
	v_add_f32_e32 v110, v141, v110
	v_add_f32_e32 v110, v142, v110
	v_add_f32_e32 v134, v143, v110
	v_cvt_pk_bf16_f32 v158, v138, v139
	v_cvt_pk_bf16_f32 v159, v140, v141
	ds_read_b64_tr_b16 v[110:111], v227 offset:29696
	ds_read_b64_tr_b16 v[112:113], v227 offset:30208
	v_add_f32_e32 v134, v144, v134
	v_add_f32_e32 v134, v145, v134
	v_add_f32_e32 v134, v66, v134
	v_add_f32_e32 v138, v67, v134
	v_cvt_pk_bf16_f32 v160, v142, v143
	v_cvt_pk_bf16_f32 v161, v144, v145
	s_waitcnt lgkmcnt(12)
	v_mfma_f32_32x32x16_bf16 v[82:97], v[178:181], v[170:173], v[82:97]
	ds_read_b64_tr_b16 v[134:135], v227 offset:26624
	ds_read_b64_tr_b16 v[136:137], v227 offset:27136
	v_add_f32_e32 v138, v68, v138
	v_add_f32_e32 v138, v69, v138
	v_add_f32_e32 v138, v70, v138
	v_add_f32_e32 v138, v71, v138
	v_cvt_pk_bf16_f32 v150, v66, v67
	v_cvt_pk_bf16_f32 v151, v68, v69
	s_waitcnt lgkmcnt(13)
	v_mfma_f32_32x32x16_bf16 v[114:129], v[182:185], v[162:165], v[114:129]
	ds_read_b64_tr_b16 v[66:67], v227 offset:30720
	ds_read_b64_tr_b16 v[68:69], v227 offset:31232
	v_add_f32_e32 v138, v72, v138
	v_add_f32_e32 v138, v73, v138
	v_add_f32_e32 v138, v74, v138
	v_add_f32_e32 v138, v75, v138
	v_cvt_pk_bf16_f32 v152, v70, v71
	v_cvt_pk_bf16_f32 v153, v72, v73
	s_waitcnt lgkmcnt(14)
	v_mfma_f32_32x32x16_bf16 v[82:97], v[186:189], v[162:165], v[82:97]
	ds_read_b64_tr_b16 v[70:71], v227 offset:27648
	ds_read_b64_tr_b16 v[72:73], v227 offset:28160
	v_add_f32_e32 v138, v76, v138
	v_add_f32_e32 v138, v77, v138
	v_add_f32_e32 v138, v78, v138
	v_add_f32_e32 v138, v79, v138
	v_cvt_pk_bf16_f32 v146, v74, v75
	v_cvt_pk_bf16_f32 v147, v76, v77
	s_waitcnt lgkmcnt(14)
	v_mfma_f32_32x32x16_bf16 v[114:129], v[210:213], v[154:157], v[114:129]
	ds_read_b64_tr_b16 v[74:75], v227 offset:31744
	ds_read_b64_tr_b16 v[76:77], v227 offset:32256
	v_mfma_f32_32x32x16_bf16 v[82:97], v[98:101], v[154:157], v[82:97]
	v_add_f32_e32 v98, v80, v138
	v_add_f32_e32 v98, v81, v98
	v_add_f32_e32 v98, 0, v98
	v_cvt_pk_bf16_f32 v148, v78, v79
	v_cvt_pk_bf16_f32 v149, v80, v81
	v_lshl_add_u64 v[78:79], v[208:209], 0, s[94:95]
	s_add_i32 s40, s40, 0xa000
	s_mov_b32 s41, m0
	s_mov_b32 m0, s40
	s_nop 0
	global_load_lds_dwordx4 v[78:79], off
	s_mov_b32 m0, s41
	v_add_f32_e32 v214, v229, v98
	s_waitcnt lgkmcnt(14)
	v_mfma_f32_32x32x16_bf16 v[18:33], v[166:169], v[102:105], v[18:33]
	v_exp_f32_e32 v114, v114
	v_exp_f32_e32 v115, v115
	v_exp_f32_e32 v116, v116
	v_exp_f32_e32 v117, v117
	s_waitcnt lgkmcnt(12)
	v_mfma_f32_32x32x16_bf16 v[34:49], v[166:169], v[130:133], v[34:49]
	v_exp_f32_e32 v118, v118
	v_exp_f32_e32 v119, v119
	v_exp_f32_e32 v120, v120
	v_exp_f32_e32 v121, v121
	ds_read_b128 v[78:81], v228 offset:16384
	ds_read_b128 v[138:141], v228 offset:16896
	s_waitcnt lgkmcnt(12)
	v_mfma_f32_32x32x16_bf16 v[18:33], v[158:161], v[106:109], v[18:33]
	v_exp_f32_e32 v122, v122
	v_exp_f32_e32 v123, v123
	v_exp_f32_e32 v124, v124
	v_exp_f32_e32 v125, v125
	ds_read_b128 v[142:145], v228 offset:18432
	ds_read_b128 v[178:181], v228 offset:18944
	s_waitcnt lgkmcnt(12)
	v_mfma_f32_32x32x16_bf16 v[34:49], v[158:161], v[110:113], v[34:49]
	v_exp_f32_e32 v126, v126
	v_exp_f32_e32 v127, v127
	v_exp_f32_e32 v128, v128
	v_exp_f32_e32 v129, v129
	ds_read_b128 v[182:185], v228 offset:20480
	ds_read_b128 v[186:189], v228 offset:20992
	s_waitcnt lgkmcnt(12)
	v_mfma_f32_32x32x16_bf16 v[18:33], v[150:153], v[134:137], v[18:33]
	v_exp_f32_e32 v82, v82
	v_exp_f32_e32 v83, v83
	v_exp_f32_e32 v84, v84
	v_exp_f32_e32 v85, v85
	ds_read_b128 v[134:137], v228 offset:22528
	ds_read_b128 v[130:133], v228 offset:23040
	s_waitcnt lgkmcnt(12)
	v_mfma_f32_32x32x16_bf16 v[34:49], v[150:153], v[66:69], v[34:49]
	v_exp_f32_e32 v86, v86
	v_exp_f32_e32 v87, v87
	v_exp_f32_e32 v88, v88
	v_exp_f32_e32 v89, v89
	s_waitcnt lgkmcnt(10)
	v_mfma_f32_32x32x16_bf16 v[18:33], v[146:149], v[70:73], v[18:33]
	v_exp_f32_e32 v90, v90
	v_exp_f32_e32 v91, v91
	v_exp_f32_e32 v92, v92
	v_exp_f32_e32 v93, v93
	s_waitcnt lgkmcnt(8)
	v_mfma_f32_32x32x16_bf16 v[34:49], v[146:149], v[74:77], v[34:49]
	v_exp_f32_e32 v94, v94
	v_exp_f32_e32 v95, v95
	v_exp_f32_e32 v96, v96
	v_exp_f32_e32 v97, v97
	s_waitcnt vmcnt(1) lgkmcnt(0)
	s_barrier
;   #define RESC() do{ if(!FIXREF&&resc){ asm volatile("s_waitcnt lgkmcnt(0)":::"memory"); \
;       _Pragma("unroll") for(int d_=0;d_<2;++d_) _Pragma("unroll") for(int r=0;r<16;++r)o[d_][r]*=wsf[crow(r,hi)]; } }while(0)
;   #define ROT() do{sl_prev=sl_cur;sl_cur=sl_next;sl_next=(sl_next==(NSLOT-1)*SLOTB)?0:sl_next+SLOTB;}while(0)
;   #define ENDW(tt) do{ if((tt)+3<NT){WAIT_BAR(2);} else if((tt)+2<NT){WAIT_BAR(1);} else {WAIT_BAR(0);} }while(0)
; template<int THRL,bool FIXREF,bool HALFK> __device__ __forceinline__ void attn_unit(float mref,long rowbase,int q0,const bf16*Qh,int PQ,const bf16*__restrict__ Kh_,int PK,const bf16*__restrict__ Vh_,int PV,bf16*Oh,int PO,const bf16*Gh,int PG,u32x4(&okeep)[4],int omode,float lam,float oml,const float ...
;     ...
;   for(;t+1<NT;t+=2){
;     STEP(pB0,pB1,pA0,pA1,t,(t+3<NT),(t+1<NT),(t+1<NT));       ENDW(t);   RESC(); ROT();
;     STEP(pA0,pA1,pB0,pB1,t+1,(t+4<NT),(t+2<NT),(t+2<NT));     ENDW(t+1); RESC(); ROT();
	ds_read_b64_tr_b16 v[210:211], v227 offset:32768
	ds_read_b64_tr_b16 v[212:213], v227 offset:33280
	v_add_f32_e32 v66, v114, v115
	v_add_f32_e32 v66, v116, v66
	v_add_f32_e32 v66, v117, v66
	v_add_f32_e32 v66, v118, v66
	v_add_f32_e32 v66, v119, v66
	v_cvt_pk_bf16_f32 v166, v114, v115
	v_cvt_pk_bf16_f32 v167, v116, v117
	s_waitcnt lgkmcnt(9)
	v_mfma_f32_32x32x16_bf16 v[98:113], v[78:81], v[174:177], v[50:65]
	ds_read_b64_tr_b16 v[114:115], v227 offset:36864
	ds_read_b64_tr_b16 v[116:117], v227 offset:37376
	v_add_f32_e32 v66, v120, v66
	v_add_f32_e32 v66, v121, v66
	v_add_f32_e32 v66, v122, v66
	v_add_f32_e32 v146, v123, v66
	s_waitcnt lgkmcnt(10)
	v_mfma_f32_32x32x16_bf16 v[66:81], v[138:141], v[174:177], v[50:65]
	v_cvt_pk_bf16_f32 v168, v118, v119
	v_cvt_pk_bf16_f32 v169, v120, v121
	ds_read_b64_tr_b16 v[138:139], v227 offset:33792
	ds_read_b64_tr_b16 v[140:141], v227 offset:34304
	v_add_f32_e32 v118, v124, v146
	v_add_f32_e32 v118, v125, v118
	v_add_f32_e32 v118, v126, v118
	v_add_f32_e32 v118, v127, v118
	v_cvt_pk_bf16_f32 v158, v122, v123
	v_cvt_pk_bf16_f32 v159, v124, v125
	s_waitcnt lgkmcnt(11)
	v_mfma_f32_32x32x16_bf16 v[98:113], v[142:145], v[170:173], v[98:113]
	ds_read_b64_tr_b16 v[120:121], v227 offset:37888
	ds_read_b64_tr_b16 v[122:123], v227 offset:38400
	s_waitcnt lgkmcnt(12)
	v_mfma_f32_32x32x16_bf16 v[66:81], v[178:181], v[170:173], v[66:81]
	v_add_f32_e32 v118, v128, v118
	v_add_f32_e32 v118, v129, v118
	v_add_f32_e32 v118, v82, v118
	v_add_f32_e32 v118, v83, v118
	v_cvt_pk_bf16_f32 v160, v126, v127
	v_cvt_pk_bf16_f32 v161, v128, v129
	ds_read_b64_tr_b16 v[124:125], v227 offset:34816
	ds_read_b64_tr_b16 v[126:127], v227 offset:35328
	v_add_f32_e32 v118, v84, v118
	v_add_f32_e32 v118, v85, v118
	v_add_f32_e32 v118, v86, v118
	v_add_f32_e32 v118, v87, v118
	v_cvt_pk_bf16_f32 v150, v82, v83
	v_cvt_pk_bf16_f32 v151, v84, v85
	s_waitcnt lgkmcnt(13)
	v_mfma_f32_32x32x16_bf16 v[98:113], v[182:185], v[162:165], v[98:113]
	ds_read_b64_tr_b16 v[82:83], v227 offset:38912
	ds_read_b64_tr_b16 v[84:85], v227 offset:39424
	s_waitcnt lgkmcnt(14)
	v_mfma_f32_32x32x16_bf16 v[66:81], v[186:189], v[162:165], v[66:81]
	v_add_f32_e32 v118, v88, v118
	v_add_f32_e32 v118, v89, v118
	v_add_f32_e32 v118, v90, v118
	v_add_f32_e32 v118, v91, v118
	v_cvt_pk_bf16_f32 v152, v86, v87
	v_cvt_pk_bf16_f32 v153, v88, v89
	ds_read_b64_tr_b16 v[86:87], v227 offset:35840
	ds_read_b64_tr_b16 v[88:89], v227 offset:36352
	v_add_f32_e32 v118, v92, v118
	v_add_f32_e32 v118, v93, v118
	v_add_f32_e32 v118, v94, v118
	v_add_f32_e32 v118, v95, v118
	v_cvt_pk_bf16_f32 v146, v90, v91
	v_cvt_pk_bf16_f32 v147, v92, v93
	s_waitcnt lgkmcnt(14)
	v_mfma_f32_32x32x16_bf16 v[98:113], v[134:137], v[154:157], v[98:113]
	ds_read_b64_tr_b16 v[90:91], v227 offset:39936
	ds_read_b64_tr_b16 v[92:93], v227 offset:40448
	v_mfma_f32_32x32x16_bf16 v[66:81], v[130:133], v[154:157], v[66:81]
	v_add_f32_e32 v118, v96, v118
	v_add_f32_e32 v118, v97, v118
	v_add_f32_e32 v118, 0, v118
	v_cvt_pk_bf16_f32 v148, v94, v95
	v_cvt_pk_bf16_f32 v149, v96, v97
	v_lshl_add_u64 v[94:95], v[208:209], 0, s[26:27]
	s_mov_b32 s40, m0
	s_mov_b32 m0, s61
	s_nop 0
	global_load_lds_dwordx4 v[94:95], off
	s_mov_b32 m0, s40
	v_add_f32_e32 v118, v214, v118
	s_waitcnt lgkmcnt(14)
	v_mfma_f32_32x32x16_bf16 v[18:33], v[166:169], v[210:213], v[18:33]
	v_exp_f32_e32 v98, v98
	v_exp_f32_e32 v99, v99
	v_exp_f32_e32 v100, v100
	v_exp_f32_e32 v101, v101
	s_waitcnt lgkmcnt(12)
	v_mfma_f32_32x32x16_bf16 v[34:49], v[166:169], v[114:117], v[34:49]
	v_exp_f32_e32 v102, v102
	v_exp_f32_e32 v103, v103
	v_exp_f32_e32 v104, v104
	v_exp_f32_e32 v105, v105
	ds_read_b128 v[128:131], v228
	ds_read_b128 v[132:135], v228 offset:512
	s_waitcnt lgkmcnt(12)
	v_mfma_f32_32x32x16_bf16 v[18:33], v[158:161], v[138:141], v[18:33]
	v_exp_f32_e32 v106, v106
	v_exp_f32_e32 v107, v107
	v_exp_f32_e32 v108, v108
	v_exp_f32_e32 v109, v109
	ds_read_b128 v[136:139], v228 offset:2048
	ds_read_b128 v[140:143], v228 offset:2560
	s_waitcnt lgkmcnt(12)
	v_mfma_f32_32x32x16_bf16 v[34:49], v[158:161], v[120:123], v[34:49]
	v_exp_f32_e32 v110, v110
	v_exp_f32_e32 v111, v111
	v_exp_f32_e32 v112, v112
	v_exp_f32_e32 v113, v113
	ds_read_b128 v[120:123], v228 offset:4096
	ds_read_b128 v[178:181], v228 offset:4608
	s_waitcnt lgkmcnt(12)
	v_mfma_f32_32x32x16_bf16 v[18:33], v[150:153], v[124:127], v[18:33]
	v_exp_f32_e32 v66, v66
	v_exp_f32_e32 v67, v67
	v_exp_f32_e32 v68, v68
	v_exp_f32_e32 v69, v69
	ds_read_b128 v[124:127], v228 offset:6144
	ds_read_b128 v[114:117], v228 offset:6656
	s_waitcnt lgkmcnt(12)
	v_mfma_f32_32x32x16_bf16 v[34:49], v[150:153], v[82:85], v[34:49]
	v_exp_f32_e32 v70, v70
	v_exp_f32_e32 v71, v71
	v_exp_f32_e32 v72, v72
	v_exp_f32_e32 v73, v73
	s_waitcnt lgkmcnt(10)
	v_mfma_f32_32x32x16_bf16 v[18:33], v[146:149], v[86:89], v[18:33]
	v_exp_f32_e32 v74, v74
	v_exp_f32_e32 v75, v75
	v_exp_f32_e32 v76, v76
	v_exp_f32_e32 v77, v77
	s_waitcnt lgkmcnt(8)
	v_mfma_f32_32x32x16_bf16 v[34:49], v[146:149], v[90:93], v[34:49]
	v_exp_f32_e32 v78, v78
	v_exp_f32_e32 v79, v79
	v_exp_f32_e32 v80, v80
	v_exp_f32_e32 v81, v81
	s_waitcnt vmcnt(0) lgkmcnt(0)
	s_barrier
;   #define RESC() do{ if(!FIXREF&&resc){ asm volatile("s_waitcnt lgkmcnt(0)":::"memory"); \
;       _Pragma("unroll") for(int d_=0;d_<2;++d_) _Pragma("unroll") for(int r=0;r<16;++r)o[d_][r]*=wsf[crow(r,hi)]; } }while(0)
; template<int THRL,bool FIXREF,bool HALFK> __device__ __forceinline__ void attn_unit(float mref,long rowbase,int q0,const bf16*Qh,int PQ,const bf16*__restrict__ Kh_,int PK,const bf16*__restrict__ Vh_,int PV,bf16*Oh,int PO,const bf16*Gh,int PG,u32x4(&okeep)[4],int omode,float lam,float oml,const float ...
;     ...
;   STEP(pB0,pB1,pA0,pA1,NT-1,false,false,false); RESC();
	ds_read_b64_tr_b16 v[182:183], v227 offset:40960
	ds_read_b64_tr_b16 v[184:185], v227 offset:41472
	v_add_f32_e32 v82, v98, v99
	v_add_f32_e32 v82, v100, v82
	v_add_f32_e32 v82, v101, v82
	v_add_f32_e32 v82, v102, v82
	v_add_f32_e32 v119, v103, v82
	v_cvt_pk_bf16_f32 v166, v98, v99
	v_cvt_pk_bf16_f32 v167, v100, v101
	s_waitcnt lgkmcnt(9)
	v_mfma_f32_32x32x16_bf16 v[82:97], v[128:131], v[174:177], v[50:65]
	ds_read_b64_tr_b16 v[98:99], v227 offset:45056
	ds_read_b64_tr_b16 v[100:101], v227 offset:45568
	v_add_f32_e32 v119, v104, v119
	v_add_f32_e32 v119, v105, v119
	v_add_f32_e32 v119, v106, v119
	v_add_f32_e32 v119, v107, v119
	v_cvt_pk_bf16_f32 v168, v102, v103
	v_cvt_pk_bf16_f32 v169, v104, v105
	s_waitcnt lgkmcnt(10)
	v_mfma_f32_32x32x16_bf16 v[50:65], v[132:135], v[174:177], v[50:65]
	ds_read_b64_tr_b16 v[102:103], v227 offset:41984
	ds_read_b64_tr_b16 v[104:105], v227 offset:42496
	v_add_f32_e32 v119, v108, v119
	v_add_f32_e32 v119, v109, v119
	v_add_f32_e32 v119, v110, v119
	v_add_f32_e32 v119, v111, v119
	v_cvt_pk_bf16_f32 v158, v106, v107
	v_cvt_pk_bf16_f32 v159, v108, v109
	s_waitcnt lgkmcnt(11)
	v_mfma_f32_32x32x16_bf16 v[82:97], v[136:139], v[170:173], v[82:97]
	ds_read_b64_tr_b16 v[106:107], v227 offset:46080
	ds_read_b64_tr_b16 v[108:109], v227 offset:46592
	v_add_f32_e32 v119, v112, v119
	v_add_f32_e32 v119, v113, v119
	v_add_f32_e32 v119, v66, v119
	v_add_f32_e32 v119, v67, v119
	v_cvt_pk_bf16_f32 v160, v110, v111
	v_cvt_pk_bf16_f32 v161, v112, v113
	s_waitcnt lgkmcnt(12)
	v_mfma_f32_32x32x16_bf16 v[50:65], v[140:143], v[170:173], v[50:65]
	ds_read_b64_tr_b16 v[110:111], v227 offset:43008
	ds_read_b64_tr_b16 v[112:113], v227 offset:43520
	v_add_f32_e32 v119, v68, v119
	v_add_f32_e32 v119, v69, v119
	v_add_f32_e32 v119, v70, v119
	v_add_f32_e32 v119, v71, v119
	v_cvt_pk_bf16_f32 v150, v66, v67
	v_cvt_pk_bf16_f32 v151, v68, v69
	s_waitcnt lgkmcnt(13)
	v_mfma_f32_32x32x16_bf16 v[82:97], v[120:123], v[162:165], v[82:97]
	ds_read_b64_tr_b16 v[66:67], v227 offset:47104
	ds_read_b64_tr_b16 v[68:69], v227 offset:47616
	v_add_f32_e32 v119, v72, v119
	v_add_f32_e32 v119, v73, v119
	v_add_f32_e32 v119, v74, v119
	v_add_f32_e32 v119, v75, v119
	v_cvt_pk_bf16_f32 v152, v70, v71
	v_cvt_pk_bf16_f32 v153, v72, v73
	s_waitcnt lgkmcnt(14)
	v_mfma_f32_32x32x16_bf16 v[50:65], v[178:181], v[162:165], v[50:65]
	ds_read_b64_tr_b16 v[70:71], v227 offset:44032
	ds_read_b64_tr_b16 v[72:73], v227 offset:44544
	v_add_f32_e32 v119, v76, v119
	v_add_f32_e32 v119, v77, v119
	v_add_f32_e32 v119, v78, v119
	v_add_f32_e32 v119, v79, v119
	v_cvt_pk_bf16_f32 v146, v74, v75
	v_cvt_pk_bf16_f32 v147, v76, v77
	s_waitcnt lgkmcnt(14)
	v_mfma_f32_32x32x16_bf16 v[82:97], v[124:127], v[154:157], v[82:97]
	ds_read_b64_tr_b16 v[74:75], v227 offset:48128
	ds_read_b64_tr_b16 v[76:77], v227 offset:48640
	v_mfma_f32_32x32x16_bf16 v[50:65], v[114:117], v[154:157], v[50:65]
	v_add_f32_e32 v114, v80, v119
	v_add_f32_e32 v114, v81, v114
	v_add_f32_e32 v114, 0, v114
	v_cvt_pk_bf16_f32 v148, v78, v79
	v_cvt_pk_bf16_f32 v149, v80, v81
	s_waitcnt lgkmcnt(14)
	v_mfma_f32_32x32x16_bf16 v[18:33], v[166:169], v[182:185], v[18:33]
	s_nop 1
	v_exp_f32_e32 v82, v82
	v_exp_f32_e32 v83, v83
	v_exp_f32_e32 v84, v84
	v_exp_f32_e32 v85, v85
	s_waitcnt lgkmcnt(12)
	v_mfma_f32_32x32x16_bf16 v[34:49], v[166:169], v[98:101], v[34:49]
	v_exp_f32_e32 v86, v86
	v_exp_f32_e32 v87, v87
	v_exp_f32_e32 v88, v88
	v_exp_f32_e32 v89, v89
	s_waitcnt lgkmcnt(10)
	v_mfma_f32_32x32x16_bf16 v[18:33], v[158:161], v[102:105], v[18:33]
	v_exp_f32_e32 v90, v90
	v_exp_f32_e32 v91, v91
	v_exp_f32_e32 v92, v92
	v_exp_f32_e32 v93, v93
	s_waitcnt lgkmcnt(8)
	v_mfma_f32_32x32x16_bf16 v[34:49], v[158:161], v[106:109], v[34:49]
	v_exp_f32_e32 v94, v94
	v_exp_f32_e32 v95, v95
	v_exp_f32_e32 v96, v96
	v_exp_f32_e32 v97, v97
	s_waitcnt lgkmcnt(6)
; #define SBAR() __builtin_amdgcn_sched_barrier(0)
;   #define RESC() do{ if(!FIXREF&&resc){ asm volatile("s_waitcnt lgkmcnt(0)":::"memory"); \
;       _Pragma("unroll") for(int d_=0;d_<2;++d_) _Pragma("unroll") for(int r=0;r<16;++r)o[d_][r]*=wsf[crow(r,hi)]; } }while(0)
;   #define PKW(P,B) cvtpk_s(P[B],P[B+1])
; template<int THRL,bool FIXREF,bool HALFK> __device__ __forceinline__ void attn_unit(float mref,long rowbase,int q0,const bf16*Qh,int PQ,const bf16*__restrict__ Kh_,int PK,const bf16*__restrict__ Vh_,int PV,bf16*Oh,int PO,const bf16*Gh,int PG,u32x4(&okeep)[4],int omode,float lam,float oml,const float ...
;     ...
;   STEP(pB0,pB1,pA0,pA1,NT-1,false,false,false); RESC();
;   { float sacc=pB0[0]+pB0[1]; _Pragma("unroll") for(int r=2;r<16;++r)sacc+=pB0[r]; _Pragma("unroll") for(int r=0;r<16;++r)sacc+=pB1[r]; l_reg+=sacc;
;     pw0=(u32x4){PKW(pB0,0),PKW(pB0,2),PKW(pB0,4),PKW(pB0,6)};pw1=(u32x4){PKW(pB0,8),PKW(pB0,10),PKW(pB0,12),PKW(pB0,14)};pw2=(u32x4){PKW(pB1,0),PKW(pB1,2),PKW(pB1,4),PKW(pB1,6)};pw3=(u32x4){PKW(pB1,8),PKW(pB1,10),PKW(pB1,12),PKW(pB1,14)};
;     SBAR(); pv(o,vb0+sl_cur,PAF(0),PAF(1),PAF(2),PAF(3)); }
;     ...
;   {auto rr=__builtin_amdgcn_permlane32_swap(__float_as_uint(l_reg),__float_as_uint(l_reg),false,false);l_reg=__uint_as_float(rr[0])+__uint_as_float(rr[1]);}
;   if(hi==0)wsf[32+r32]=l_reg;asm volatile("s_waitcnt lgkmcnt(0)":::"memory");
	v_mfma_f32_32x32x16_bf16 v[18:33], v[150:153], v[110:113], v[18:33]
	v_exp_f32_e32 v50, v50
	v_exp_f32_e32 v51, v51
	v_exp_f32_e32 v52, v52
	v_exp_f32_e32 v53, v53
	s_waitcnt lgkmcnt(4)
	v_mfma_f32_32x32x16_bf16 v[34:49], v[150:153], v[66:69], v[34:49]
	v_exp_f32_e32 v54, v54
	v_exp_f32_e32 v55, v55
	v_exp_f32_e32 v56, v56
	v_exp_f32_e32 v57, v57
	s_waitcnt lgkmcnt(2)
	v_mfma_f32_32x32x16_bf16 v[18:33], v[146:149], v[70:73], v[18:33]
	v_exp_f32_e32 v58, v58
	v_exp_f32_e32 v59, v59
	v_exp_f32_e32 v60, v60
	v_exp_f32_e32 v61, v61
	s_waitcnt lgkmcnt(0)
	v_mfma_f32_32x32x16_bf16 v[34:49], v[146:149], v[74:77], v[34:49]
	v_exp_f32_e32 v62, v62
	v_exp_f32_e32 v63, v63
	v_exp_f32_e32 v64, v64
	v_exp_f32_e32 v65, v65
	v_add_f32_e32 v66, v82, v83
	v_add_f32_e32 v66, v84, v66
	v_add_f32_e32 v66, v85, v66
	v_add_f32_e32 v66, v86, v66
	v_add_f32_e32 v66, v87, v66
	v_add_f32_e32 v66, v88, v66
	v_add_f32_e32 v66, v89, v66
	v_add_f32_e32 v66, v90, v66
	v_add_f32_e32 v66, v91, v66
	v_add_f32_e32 v66, v92, v66
	v_add_f32_e32 v66, v93, v66
	v_add_f32_e32 v66, v94, v66
	v_add_f32_e32 v66, v95, v66
	v_add_f32_e32 v66, v96, v66
	v_add_f32_e32 v66, v97, v66
	v_add_f32_e32 v66, v50, v66
	v_add_f32_e32 v66, v51, v66
	v_add_f32_e32 v66, v52, v66
	v_add_f32_e32 v66, v53, v66
	v_add_f32_e32 v66, v54, v66
	v_add_f32_e32 v66, v55, v66
	v_add_f32_e32 v66, v56, v66
	v_add_f32_e32 v66, v57, v66
	v_add_f32_e32 v66, v58, v66
	v_add_f32_e32 v66, v59, v66
	v_add_f32_e32 v66, v60, v66
	v_add_f32_e32 v66, v61, v66
	v_add_f32_e32 v66, v62, v66
	v_add_f32_e32 v66, v63, v66
	v_add_f32_e32 v66, v64, v66
	v_add_f32_e32 v66, v65, v66
	v_add_f32_e32 v67, v118, v114
	v_add_f32_e32 v66, v67, v66
	v_cvt_pk_bf16_f32 v68, v82, v83
	v_cvt_pk_bf16_f32 v69, v84, v85
	v_cvt_pk_bf16_f32 v70, v86, v87
	v_cvt_pk_bf16_f32 v71, v88, v89
	v_cvt_pk_bf16_f32 v72, v90, v91
	v_cvt_pk_bf16_f32 v73, v92, v93
	v_cvt_pk_bf16_f32 v74, v94, v95
	v_cvt_pk_bf16_f32 v75, v96, v97
	v_cvt_pk_bf16_f32 v50, v50, v51
	v_cvt_pk_bf16_f32 v51, v52, v53
	v_cvt_pk_bf16_f32 v52, v54, v55
	v_cvt_pk_bf16_f32 v53, v56, v57
	v_cvt_pk_bf16_f32 v54, v58, v59
	v_cvt_pk_bf16_f32 v55, v60, v61
	v_cvt_pk_bf16_f32 v56, v62, v63
	v_cvt_pk_bf16_f32 v57, v64, v65
	ds_read_b64_tr_b16 v[58:59],v0 offset:0
	ds_read_b64_tr_b16 v[60:61],v0 offset:512
	ds_read_b64_tr_b16 v[62:63],v0 offset:1024
	ds_read_b64_tr_b16 v[64:65],v0 offset:1536
	ds_read_b64_tr_b16 v[76:77],v0 offset:2048
	ds_read_b64_tr_b16 v[78:79],v0 offset:2560
	ds_read_b64_tr_b16 v[80:81],v0 offset:3072
	ds_read_b64_tr_b16 v[82:83],v0 offset:3584
	s_waitcnt lgkmcnt(0)
	s_nop 0
	v_mfma_f32_32x32x16_bf16 v[18:33], v[68:71], v[58:61], v[18:33]
	ds_read_b64_tr_b16 v[58:59],v0 offset:4096
	ds_read_b64_tr_b16 v[60:61],v0 offset:4608
	v_mfma_f32_32x32x16_bf16 v[18:33], v[72:75], v[62:65], v[18:33]
	ds_read_b64_tr_b16 v[62:63],v0 offset:5120
	ds_read_b64_tr_b16 v[64:65],v0 offset:5632
	v_mfma_f32_32x32x16_bf16 v[18:33], v[50:53], v[76:79], v[18:33]
	ds_read_b64_tr_b16 v[76:77],v0 offset:6144
	ds_read_b64_tr_b16 v[78:79],v0 offset:6656
	v_mfma_f32_32x32x16_bf16 v[18:33], v[54:57], v[80:83], v[18:33]
	ds_read_b64_tr_b16 v[80:81],v0 offset:7168
	ds_read_b64_tr_b16 v[82:83],v0 offset:7680
	s_waitcnt lgkmcnt(0)
	v_mfma_f32_32x32x16_bf16 v[34:49], v[68:71], v[58:61], v[34:49]
	v_mov_b32_e32 v0, v66
	s_nop 1
	v_permlane32_swap_b32_e32 v66, v0
	v_cmp_gt_u32_e32 vcc, 32, v205
	v_mfma_f32_32x32x16_bf16 v[34:49], v[72:75], v[62:65], v[34:49]
	v_mfma_f32_32x32x16_bf16 v[34:49], v[50:53], v[76:79], v[34:49]
	v_mfma_f32_32x32x16_bf16 v[34:49], v[54:57], v[80:83], v[34:49]
	s_and_saveexec_b64 s[40:41], vcc
	s_cbranch_execz .LBB0_449
	v_lshl_add_u32 v50, v216, 2, s42
	v_add_f32_e32 v0, v66, v0
	ds_write_b32 v50, v0 offset:49280
	s_branch .LBB0_449

; #define WAIT_BAR(N) asm volatile("s_waitcnt vmcnt(" #N ") lgkmcnt(0)\n\ts_barrier":::"memory")
;   #define RESC() do{ if(!FIXREF&&resc){ asm volatile("s_waitcnt lgkmcnt(0)":::"memory"); \
;       _Pragma("unroll") for(int d_=0;d_<2;++d_) _Pragma("unroll") for(int r=0;r<16;++r)o[d_][r]*=wsf[crow(r,hi)]; } }while(0)
;   #define ROT() do{sl_prev=sl_cur;sl_cur=sl_next;sl_next=(sl_next==(NSLOT-1)*SLOTB)?0:sl_next+SLOTB;}while(0)
; template<int THRL,bool FIXREF,bool HALFK> __device__ __forceinline__ void attn_unit(float mref,long rowbase,int q0,const bf16*Qh,int PQ,const bf16*__restrict__ Kh_,int PK,const bf16*__restrict__ Vh_,int PV,bf16*Oh,int PO,const bf16*Gh,int PG,u32x4(&okeep)[4],int omode,float lam,float oml,const float ...
;     ...
;   for(;t+5<NT;t+=2){
;     STEP(pB0,pB1,pA0,pA1,t,true,true,true);     WAIT_BAR(2); RESC(); ROT();
;     STEP(pA0,pA1,pB0,pB1,t+1,true,true,true);   WAIT_BAR(2); RESC(); ROT();
.LBB0_461:
	v_add_u32_e32 v0, s87, v213
	ds_read_b64_tr_b16 v[228:229], v0 offset:24576
	ds_read_b64_tr_b16 v[230:231], v0 offset:25088
	v_add_f32_e32 v102, v82, v83
	v_add_f32_e32 v102, v84, v102
	v_add_f32_e32 v102, v85, v102
	v_add_f32_e32 v102, v86, v102
	v_add_f32_e32 v102, v87, v102
	v_cvt_pk_bf16_f32 v158, v82, v83
	v_cvt_pk_bf16_f32 v159, v84, v85
	s_waitcnt lgkmcnt(5)
	v_mfma_f32_32x32x16_bf16 v[114:129], v[98:101], v[166:169], v[50:65]
	ds_read_b64_tr_b16 v[82:83], v0 offset:28672
	ds_read_b64_tr_b16 v[84:85], v0 offset:29184
	v_add_f32_e32 v98, v88, v102
	v_add_f32_e32 v98, v89, v98
	v_add_f32_e32 v98, v90, v98
	v_add_f32_e32 v146, v91, v98
	s_waitcnt lgkmcnt(6)
	v_mfma_f32_32x32x16_bf16 v[98:113], v[134:137], v[166:169], v[50:65]
	v_cvt_pk_bf16_f32 v160, v86, v87
	v_cvt_pk_bf16_f32 v161, v88, v89
	ds_read_b64_tr_b16 v[86:87], v0 offset:25600
	ds_read_b64_tr_b16 v[88:89], v0 offset:26112
	v_add_f32_e32 v134, v92, v146
	v_add_f32_e32 v134, v93, v134
	v_add_f32_e32 v134, v94, v134
	v_add_f32_e32 v134, v95, v134
	v_cvt_pk_bf16_f32 v154, v90, v91
	v_cvt_pk_bf16_f32 v155, v92, v93
	s_waitcnt lgkmcnt(7)
	v_mfma_f32_32x32x16_bf16 v[114:129], v[138:141], v[162:165], v[114:129]
	ds_read_b64_tr_b16 v[90:91], v0 offset:29696
	ds_read_b64_tr_b16 v[92:93], v0 offset:30208
	s_waitcnt lgkmcnt(8)
	v_mfma_f32_32x32x16_bf16 v[98:113], v[130:133], v[162:165], v[98:113]
	v_add_f32_e32 v130, v96, v134
	v_add_f32_e32 v130, v97, v130
	v_add_f32_e32 v130, v66, v130
	v_add_f32_e32 v130, v67, v130
	v_cvt_pk_bf16_f32 v156, v94, v95
	v_cvt_pk_bf16_f32 v157, v96, v97
	ds_read_b64_tr_b16 v[94:95], v0 offset:26624
	ds_read_b64_tr_b16 v[96:97], v0 offset:27136
	v_add_f32_e32 v130, v68, v130
	v_add_f32_e32 v130, v69, v130
	v_add_f32_e32 v130, v70, v130
	v_add_f32_e32 v130, v71, v130
	v_cvt_pk_bf16_f32 v150, v66, v67
	v_cvt_pk_bf16_f32 v151, v68, v69
	ds_read_b64_tr_b16 v[66:67], v0 offset:30720
	ds_read_b64_tr_b16 v[68:69], v0 offset:31232
	v_add_f32_e32 v130, v72, v130
	v_add_f32_e32 v130, v73, v130
	v_add_f32_e32 v130, v74, v130
	v_add_f32_e32 v130, v75, v130
	v_cvt_pk_bf16_f32 v152, v70, v71
	v_cvt_pk_bf16_f32 v153, v72, v73
	ds_read_b64_tr_b16 v[70:71], v0 offset:27648
	ds_read_b64_tr_b16 v[72:73], v0 offset:28160
	v_add_f32_e32 v130, v76, v130
	v_add_f32_e32 v130, v77, v130
	v_add_f32_e32 v130, v78, v130
	v_add_f32_e32 v130, v79, v130
	v_cvt_pk_bf16_f32 v146, v74, v75
	v_cvt_pk_bf16_f32 v147, v76, v77
	ds_read_b64_tr_b16 v[74:75], v0 offset:31744
	ds_read_b64_tr_b16 v[76:77], v0 offset:32256
	v_add_f32_e32 v0, v80, v130
	v_add_f32_e32 v0, v81, v0
	v_cvt_pk_bf16_f32 v148, v78, v79
	v_cvt_pk_bf16_f32 v149, v80, v81
	v_lshl_add_u64 v[78:79], v[144:145], 0, s[36:37]
	s_add_i32 s20, s86, s81
	s_mov_b32 s48, m0
	s_mov_b32 m0, s20
	s_nop 0
	global_load_lds_dwordx4 v[78:79], off
	s_mov_b32 m0, s48
	v_lshl_add_u64 v[78:79], v[142:143], 0, s[22:23]
	s_add_i32 s20, s85, s80
	s_mov_b32 s48, m0
	s_mov_b32 m0, s20
	s_nop 0
	global_load_lds_dwordx4 v[78:79], off
	s_mov_b32 m0, s48
	v_add_f32_e32 v0, v227, v0
	s_waitcnt lgkmcnt(14)
	v_mfma_f32_32x32x16_bf16 v[18:33], v[158:161], v[228:231], v[18:33]
	v_exp_f32_e32 v114, v114
	v_exp_f32_e32 v115, v115
	v_exp_f32_e32 v116, v116
	v_exp_f32_e32 v117, v117
	s_waitcnt lgkmcnt(12)
	v_mfma_f32_32x32x16_bf16 v[34:49], v[158:161], v[82:85], v[34:49]
	v_exp_f32_e32 v118, v118
	v_exp_f32_e32 v119, v119
	v_exp_f32_e32 v120, v120
	v_exp_f32_e32 v121, v121
	v_add_u32_e32 v82, s85, v214
	ds_read_b128 v[78:81], v82
	ds_read_b128 v[130:133], v82 offset:512
	s_waitcnt lgkmcnt(12)
	v_mfma_f32_32x32x16_bf16 v[18:33], v[154:157], v[86:89], v[18:33]
	v_exp_f32_e32 v122, v122
	v_exp_f32_e32 v123, v123
	v_exp_f32_e32 v124, v124
	v_exp_f32_e32 v125, v125
	ds_read_b128 v[134:137], v82 offset:2048
	ds_read_b128 v[138:141], v82 offset:2560
	s_waitcnt lgkmcnt(12)
	v_mfma_f32_32x32x16_bf16 v[34:49], v[154:157], v[90:93], v[34:49]
	v_exp_f32_e32 v126, v126
	v_exp_f32_e32 v127, v127
	v_exp_f32_e32 v128, v128
	v_exp_f32_e32 v129, v129
	s_waitcnt lgkmcnt(10)
	v_mfma_f32_32x32x16_bf16 v[18:33], v[150:153], v[94:97], v[18:33]
	v_exp_f32_e32 v98, v98
	v_exp_f32_e32 v99, v99
	v_exp_f32_e32 v100, v100
	v_exp_f32_e32 v101, v101
	s_waitcnt lgkmcnt(8)
	v_mfma_f32_32x32x16_bf16 v[34:49], v[150:153], v[66:69], v[34:49]
	v_exp_f32_e32 v102, v102
	v_exp_f32_e32 v103, v103
	v_exp_f32_e32 v104, v104
	v_exp_f32_e32 v105, v105
	s_waitcnt lgkmcnt(6)
	v_mfma_f32_32x32x16_bf16 v[18:33], v[146:149], v[70:73], v[18:33]
	v_exp_f32_e32 v106, v106
	v_exp_f32_e32 v107, v107
	v_exp_f32_e32 v108, v108
	v_exp_f32_e32 v109, v109
	s_waitcnt lgkmcnt(4)
	v_mfma_f32_32x32x16_bf16 v[34:49], v[146:149], v[74:77], v[34:49]
	v_exp_f32_e32 v110, v110
	v_exp_f32_e32 v111, v111
	v_exp_f32_e32 v112, v112
	v_exp_f32_e32 v113, v113
	s_add_i32 s20, s85, 0x2000
	s_cmpk_lg_i32 s85, 0x4000
	s_cselect_b32 s20, s20, 0
	v_add_u32_e32 v227, s86, v213
	s_waitcnt vmcnt(2) lgkmcnt(0)
	s_barrier
; #define WAIT_BAR(N) asm volatile("s_waitcnt vmcnt(" #N ") lgkmcnt(0)\n\ts_barrier":::"memory")
;   #define RESC() do{ if(!FIXREF&&resc){ asm volatile("s_waitcnt lgkmcnt(0)":::"memory"); \
;       _Pragma("unroll") for(int d_=0;d_<2;++d_) _Pragma("unroll") for(int r=0;r<16;++r)o[d_][r]*=wsf[crow(r,hi)]; } }while(0)
;   #define ROT() do{sl_prev=sl_cur;sl_cur=sl_next;sl_next=(sl_next==(NSLOT-1)*SLOTB)?0:sl_next+SLOTB;}while(0)
; template<int THRL,bool FIXREF,bool HALFK> __device__ __forceinline__ void attn_unit(float mref,long rowbase,int q0,const bf16*Qh,int PQ,const bf16*__restrict__ Kh_,int PK,const bf16*__restrict__ Vh_,int PV,bf16*Oh,int PO,const bf16*Gh,int PG,u32x4(&okeep)[4],int omode,float lam,float oml,const float ...
;     ...
;   for(;t+5<NT;t+=2){
;     STEP(pB0,pB1,pA0,pA1,t,true,true,true);     WAIT_BAR(2); RESC(); ROT();
;     STEP(pA0,pA1,pB0,pB1,t+1,true,true,true);   WAIT_BAR(2); RESC(); ROT();
	ds_read_b64_tr_b16 v[228:229], v227 offset:24576
	ds_read_b64_tr_b16 v[230:231], v227 offset:25088
	s_waitcnt lgkmcnt(5)
	v_mfma_f32_32x32x16_bf16 v[82:97], v[78:81], v[166:169], v[50:65]
	v_add_f32_e32 v66, v114, v115
	v_add_f32_e32 v66, v116, v66
	v_add_f32_e32 v66, v117, v66
	v_add_f32_e32 v66, v118, v66
	v_add_f32_e32 v66, v119, v66
	v_cvt_pk_bf16_f32 v158, v114, v115
	v_cvt_pk_bf16_f32 v159, v116, v117
	ds_read_b64_tr_b16 v[114:115], v227 offset:28672
	ds_read_b64_tr_b16 v[116:117], v227 offset:29184
	v_add_f32_e32 v66, v120, v66
	v_add_f32_e32 v66, v121, v66
	v_add_f32_e32 v66, v122, v66
	v_add_f32_e32 v146, v123, v66
	s_waitcnt lgkmcnt(6)
	v_mfma_f32_32x32x16_bf16 v[66:81], v[130:133], v[166:169], v[50:65]
	v_cvt_pk_bf16_f32 v160, v118, v119
	v_cvt_pk_bf16_f32 v161, v120, v121
	ds_read_b64_tr_b16 v[118:119], v227 offset:25600
	ds_read_b64_tr_b16 v[120:121], v227 offset:26112
	s_waitcnt lgkmcnt(7)
	v_mfma_f32_32x32x16_bf16 v[82:97], v[134:137], v[162:165], v[82:97]
	v_add_f32_e32 v130, v124, v146
	v_add_f32_e32 v130, v125, v130
	v_add_f32_e32 v130, v126, v130
	v_add_f32_e32 v130, v127, v130
	v_cvt_pk_bf16_f32 v154, v122, v123
	v_cvt_pk_bf16_f32 v155, v124, v125
	ds_read_b64_tr_b16 v[122:123], v227 offset:29696
	ds_read_b64_tr_b16 v[124:125], v227 offset:30208
	s_waitcnt lgkmcnt(8)
	v_mfma_f32_32x32x16_bf16 v[66:81], v[138:141], v[162:165], v[66:81]
	v_add_f32_e32 v130, v128, v130
	v_add_f32_e32 v130, v129, v130
	v_add_f32_e32 v130, v98, v130
	v_add_f32_e32 v130, v99, v130
	v_cvt_pk_bf16_f32 v156, v126, v127
	v_cvt_pk_bf16_f32 v157, v128, v129
	ds_read_b64_tr_b16 v[126:127], v227 offset:26624
	ds_read_b64_tr_b16 v[128:129], v227 offset:27136
	v_add_f32_e32 v130, v100, v130
	v_add_f32_e32 v130, v101, v130
	v_add_f32_e32 v130, v102, v130
	v_add_f32_e32 v130, v103, v130
	v_cvt_pk_bf16_f32 v150, v98, v99
	v_cvt_pk_bf16_f32 v151, v100, v101
	ds_read_b64_tr_b16 v[232:233], v227 offset:30720
	ds_read_b64_tr_b16 v[234:235], v227 offset:31232
	v_add_f32_e32 v98, v104, v130
	v_add_f32_e32 v98, v105, v98
	v_add_f32_e32 v98, v106, v98
	v_add_f32_e32 v98, v107, v98
	v_cvt_pk_bf16_f32 v152, v102, v103
	v_cvt_pk_bf16_f32 v153, v104, v105
	ds_read_b64_tr_b16 v[102:103], v227 offset:27648
	ds_read_b64_tr_b16 v[104:105], v227 offset:28160
	v_add_f32_e32 v98, v108, v98
	v_add_f32_e32 v98, v109, v98
	v_add_f32_e32 v98, v110, v98
	v_add_f32_e32 v98, v111, v98
	v_cvt_pk_bf16_f32 v146, v106, v107
	v_cvt_pk_bf16_f32 v147, v108, v109
	ds_read_b64_tr_b16 v[106:107], v227 offset:31744
	ds_read_b64_tr_b16 v[108:109], v227 offset:32256
	v_add_f32_e32 v98, v112, v98
	v_add_f32_e32 v98, v113, v98
	v_cvt_pk_bf16_f32 v148, v110, v111
	v_cvt_pk_bf16_f32 v149, v112, v113
	s_nop 0
	v_add_f32_e32 v227, v0, v98
	v_lshl_add_u64 v[98:99], v[144:145], 0, s[96:97]
	s_add_i32 s48, s85, s81
	s_mov_b32 s49, m0
	s_mov_b32 m0, s48
	s_nop 0
	global_load_lds_dwordx4 v[98:99], off
	s_mov_b32 m0, s49
	v_lshl_add_u64 v[142:143], v[142:143], 0, s[4:5]
	s_add_i32 s48, s20, s80
	s_mov_b32 s49, m0
	s_mov_b32 m0, s48
	s_nop 0
	global_load_lds_dwordx4 v[142:143], off
	s_mov_b32 m0, s49
	s_waitcnt lgkmcnt(14)
	v_mfma_f32_32x32x16_bf16 v[18:33], v[158:161], v[228:231], v[18:33]
	v_exp_f32_e32 v82, v82
	v_exp_f32_e32 v83, v83
	v_exp_f32_e32 v84, v84
	v_exp_f32_e32 v85, v85
	s_waitcnt lgkmcnt(12)
	v_mfma_f32_32x32x16_bf16 v[34:49], v[158:161], v[114:117], v[34:49]
	v_exp_f32_e32 v86, v86
	v_exp_f32_e32 v87, v87
	v_exp_f32_e32 v88, v88
	v_exp_f32_e32 v89, v89
	v_add_u32_e32 v0, s20, v214
	ds_read_b128 v[98:101], v0
	ds_read_b128 v[134:137], v0 offset:512
	s_waitcnt lgkmcnt(12)
	v_mfma_f32_32x32x16_bf16 v[18:33], v[154:157], v[118:121], v[18:33]
	v_exp_f32_e32 v90, v90
	v_exp_f32_e32 v91, v91
	v_exp_f32_e32 v92, v92
	v_exp_f32_e32 v93, v93
	ds_read_b128 v[138:141], v0 offset:2048
	ds_read_b128 v[130:133], v0 offset:2560
	s_waitcnt lgkmcnt(12)
	v_mfma_f32_32x32x16_bf16 v[34:49], v[154:157], v[122:125], v[34:49]
	v_exp_f32_e32 v94, v94
	v_exp_f32_e32 v95, v95
	v_exp_f32_e32 v96, v96
	v_exp_f32_e32 v97, v97
	s_waitcnt lgkmcnt(10)
	v_mfma_f32_32x32x16_bf16 v[18:33], v[150:153], v[126:129], v[18:33]
	v_exp_f32_e32 v66, v66
	v_exp_f32_e32 v67, v67
	v_exp_f32_e32 v68, v68
	v_exp_f32_e32 v69, v69
	s_waitcnt lgkmcnt(8)
	v_mfma_f32_32x32x16_bf16 v[34:49], v[150:153], v[232:235], v[34:49]
	v_exp_f32_e32 v70, v70
	v_exp_f32_e32 v71, v71
	v_exp_f32_e32 v72, v72
	v_exp_f32_e32 v73, v73
	s_waitcnt lgkmcnt(6)
	v_mfma_f32_32x32x16_bf16 v[18:33], v[146:149], v[102:105], v[18:33]
	v_exp_f32_e32 v74, v74
	v_exp_f32_e32 v75, v75
	v_exp_f32_e32 v76, v76
	v_exp_f32_e32 v77, v77
	s_waitcnt lgkmcnt(4)
	v_mfma_f32_32x32x16_bf16 v[34:49], v[146:149], v[106:109], v[34:49]
	v_exp_f32_e32 v78, v78
	v_exp_f32_e32 v79, v79
	v_exp_f32_e32 v80, v80
	v_exp_f32_e32 v81, v81
	s_add_i32 s48, s20, 0x2000
	s_cmpk_lg_i32 s20, 0x4000
	s_mov_b32 s87, s85
	s_cselect_b32 s85, s48, 0
	s_add_i32 s84, s84, 2
	v_lshl_add_u64 v[144:145], v[144:145], 0, s[92:93]
	s_mov_b32 s86, s20
	s_cmp_gt_u32 s84, 56
	s_waitcnt vmcnt(2) lgkmcnt(0)
	s_barrier
	s_cbranch_scc0 .LBB0_461
;   #define RESC() do{ if(!FIXREF&&resc){ asm volatile("s_waitcnt lgkmcnt(0)":::"memory"); \
;       _Pragma("unroll") for(int d_=0;d_<2;++d_) _Pragma("unroll") for(int r=0;r<16;++r)o[d_][r]*=wsf[crow(r,hi)]; } }while(0)
;   #define ROT() do{sl_prev=sl_cur;sl_cur=sl_next;sl_next=(sl_next==(NSLOT-1)*SLOTB)?0:sl_next+SLOTB;}while(0)
;   #define ENDW(tt) do{ if((tt)+3<NT){WAIT_BAR(2);} else if((tt)+2<NT){WAIT_BAR(1);} else {WAIT_BAR(0);} }while(0)
; template<int THRL,bool FIXREF,bool HALFK> __device__ __forceinline__ void attn_unit(float mref,long rowbase,int q0,const bf16*Qh,int PQ,const bf16*__restrict__ Kh_,int PK,const bf16*__restrict__ Vh_,int PV,bf16*Oh,int PO,const bf16*Gh,int PG,u32x4(&okeep)[4],int omode,float lam,float oml,const float ...
;     ...
;   for(;t+1<NT;t+=2){
;     STEP(pB0,pB1,pA0,pA1,t,(t+3<NT),(t+1<NT),(t+1<NT));       ENDW(t);   RESC(); ROT();
;     STEP(pA0,pA1,pB0,pB1,t+1,(t+4<NT),(t+2<NT),(t+2<NT));     ENDW(t+1); RESC(); ROT();
	s_and_b32 s20, s83, 0x3fffffc0
	s_lshl_b32 s20, s20, 2
	s_add_i32 s20, s20, 0
	s_cmp_lg_u32 0, -1
	s_cselect_b32 s50, 0, 0
	s_add_i32 s48, s50, 0x6000
	v_add_u32_e32 v0, s48, v216
	v_add3_u32 v0, v0, v215, v217
	ds_read_b64_tr_b16 v[142:143], v213 offset:32768
	ds_read_b64_tr_b16 v[144:145], v213 offset:33280
	v_add_f32_e32 v102, v82, v83
	v_add_f32_e32 v102, v84, v102
	v_add_f32_e32 v102, v85, v102
	v_add_f32_e32 v102, v86, v102
	v_add_f32_e32 v102, v87, v102
	v_cvt_pk_bf16_f32 v158, v82, v83
	v_cvt_pk_bf16_f32 v159, v84, v85
	s_waitcnt lgkmcnt(5)
	v_mfma_f32_32x32x16_bf16 v[114:129], v[98:101], v[166:169], v[50:65]
	ds_read_b64_tr_b16 v[82:83], v213 offset:36864
	ds_read_b64_tr_b16 v[84:85], v213 offset:37376
	v_add_f32_e32 v98, v88, v102
	v_add_f32_e32 v98, v89, v98
	v_add_f32_e32 v98, v90, v98
	v_add_f32_e32 v146, v91, v98
	v_cvt_pk_bf16_f32 v160, v86, v87
	v_cvt_pk_bf16_f32 v161, v88, v89
	s_waitcnt lgkmcnt(6)
	v_mfma_f32_32x32x16_bf16 v[98:113], v[134:137], v[166:169], v[50:65]
	ds_read_b64_tr_b16 v[86:87], v213 offset:33792
	ds_read_b64_tr_b16 v[88:89], v213 offset:34304
	v_add_f32_e32 v134, v92, v146
	v_add_f32_e32 v134, v93, v134
	v_add_f32_e32 v134, v94, v134
	v_add_f32_e32 v134, v95, v134
	v_cvt_pk_bf16_f32 v154, v90, v91
	v_cvt_pk_bf16_f32 v155, v92, v93
	s_waitcnt lgkmcnt(7)
	v_mfma_f32_32x32x16_bf16 v[114:129], v[138:141], v[162:165], v[114:129]
	ds_read_b64_tr_b16 v[90:91], v213 offset:37888
	ds_read_b64_tr_b16 v[92:93], v213 offset:38400
	s_waitcnt lgkmcnt(8)
	v_mfma_f32_32x32x16_bf16 v[98:113], v[130:133], v[162:165], v[98:113]
	v_add_f32_e32 v130, v96, v134
	v_add_f32_e32 v130, v97, v130
	v_add_f32_e32 v130, v66, v130
	v_add_f32_e32 v130, v67, v130
	v_cvt_pk_bf16_f32 v156, v94, v95
	v_cvt_pk_bf16_f32 v157, v96, v97
	ds_read_b64_tr_b16 v[94:95], v213 offset:34816
	ds_read_b64_tr_b16 v[96:97], v213 offset:35328
	v_add_f32_e32 v130, v68, v130
	v_add_f32_e32 v130, v69, v130
	v_add_f32_e32 v130, v70, v130
	v_add_f32_e32 v130, v71, v130
	v_cvt_pk_bf16_f32 v150, v66, v67
	v_cvt_pk_bf16_f32 v151, v68, v69
	ds_read_b64_tr_b16 v[66:67], v213 offset:38912
	ds_read_b64_tr_b16 v[68:69], v213 offset:39424
	v_add_f32_e32 v130, v72, v130
	v_add_f32_e32 v130, v73, v130
	v_add_f32_e32 v130, v74, v130
	v_add_f32_e32 v130, v75, v130
	v_cvt_pk_bf16_f32 v152, v70, v71
	v_cvt_pk_bf16_f32 v153, v72, v73
	ds_read_b64_tr_b16 v[70:71], v213 offset:35840
	ds_read_b64_tr_b16 v[72:73], v213 offset:36352
	v_add_f32_e32 v130, v76, v130
	v_add_f32_e32 v130, v77, v130
	v_add_f32_e32 v130, v78, v130
	v_add_f32_e32 v130, v79, v130
	v_cvt_pk_bf16_f32 v146, v74, v75
	v_cvt_pk_bf16_f32 v147, v76, v77
	ds_read_b64_tr_b16 v[74:75], v213 offset:39936
	ds_read_b64_tr_b16 v[76:77], v213 offset:40448
	v_add_f32_e32 v130, v80, v130
	v_add_f32_e32 v130, v81, v130
	v_add_f32_e32 v130, 0, v130
	v_cvt_pk_bf16_f32 v148, v78, v79
	v_cvt_pk_bf16_f32 v149, v80, v81
	s_mov_b64 s[48:49], 0x1f0000
	v_lshl_add_u64 v[78:79], v[174:175], 0, s[48:49]
	s_add_i32 s48, s50, s82
	s_add_i32 s49, s48, 0x4000
	s_mov_b32 s50, m0
	s_mov_b32 m0, s49
	s_nop 0
	global_load_lds_dwordx4 v[78:79], off
	s_mov_b32 m0, s50
	v_lshl_add_u64 v[78:79], v[172:173], 0, s[18:19]
	s_mov_b32 s49, m0
	s_mov_b32 m0, s80
	s_nop 0
	global_load_lds_dwordx4 v[78:79], off
	s_mov_b32 m0, s49
	v_add_f32_e32 v215, v227, v130
	s_waitcnt lgkmcnt(14)
	v_mfma_f32_32x32x16_bf16 v[18:33], v[158:161], v[142:145], v[18:33]
	v_exp_f32_e32 v114, v114
	v_exp_f32_e32 v115, v115
	v_exp_f32_e32 v116, v116
	v_exp_f32_e32 v117, v117
	s_waitcnt lgkmcnt(12)
	v_mfma_f32_32x32x16_bf16 v[34:49], v[158:161], v[82:85], v[34:49]
	v_exp_f32_e32 v118, v118
	v_exp_f32_e32 v119, v119
	v_exp_f32_e32 v120, v120
	v_exp_f32_e32 v121, v121
	ds_read_b128 v[78:81], v214
	ds_read_b128 v[82:85], v214 offset:512
	s_waitcnt lgkmcnt(12)
	v_mfma_f32_32x32x16_bf16 v[18:33], v[154:157], v[86:89], v[18:33]
	v_exp_f32_e32 v122, v122
	v_exp_f32_e32 v123, v123
	v_exp_f32_e32 v124, v124
	v_exp_f32_e32 v125, v125
	ds_read_b128 v[86:89], v214 offset:2048
	ds_read_b128 v[228:231], v214 offset:2560
	s_waitcnt lgkmcnt(12)
	v_mfma_f32_32x32x16_bf16 v[34:49], v[154:157], v[90:93], v[34:49]
	v_exp_f32_e32 v126, v126
	v_exp_f32_e32 v127, v127
	v_exp_f32_e32 v128, v128
	v_exp_f32_e32 v129, v129
	s_waitcnt lgkmcnt(10)
	v_mfma_f32_32x32x16_bf16 v[18:33], v[150:153], v[94:97], v[18:33]
	v_exp_f32_e32 v98, v98
	v_exp_f32_e32 v99, v99
	v_exp_f32_e32 v100, v100
	v_exp_f32_e32 v101, v101
	s_waitcnt lgkmcnt(8)
	v_mfma_f32_32x32x16_bf16 v[34:49], v[150:153], v[66:69], v[34:49]
	v_exp_f32_e32 v102, v102
	v_exp_f32_e32 v103, v103
	v_exp_f32_e32 v104, v104
	v_exp_f32_e32 v105, v105
	s_waitcnt lgkmcnt(6)
	v_mfma_f32_32x32x16_bf16 v[18:33], v[146:149], v[70:73], v[18:33]
	v_exp_f32_e32 v106, v106
	v_exp_f32_e32 v107, v107
	v_exp_f32_e32 v108, v108
	v_exp_f32_e32 v109, v109
	s_waitcnt lgkmcnt(4)
	v_mfma_f32_32x32x16_bf16 v[34:49], v[146:149], v[74:77], v[34:49]
	v_exp_f32_e32 v110, v110
	v_exp_f32_e32 v111, v111
	v_exp_f32_e32 v112, v112
	v_exp_f32_e32 v113, v113
	s_waitcnt vmcnt(2) lgkmcnt(0)
	s_barrier
;   #define RESC() do{ if(!FIXREF&&resc){ asm volatile("s_waitcnt lgkmcnt(0)":::"memory"); \
;       _Pragma("unroll") for(int d_=0;d_<2;++d_) _Pragma("unroll") for(int r=0;r<16;++r)o[d_][r]*=wsf[crow(r,hi)]; } }while(0)
;   #define ROT() do{sl_prev=sl_cur;sl_cur=sl_next;sl_next=(sl_next==(NSLOT-1)*SLOTB)?0:sl_next+SLOTB;}while(0)
;   #define ENDW(tt) do{ if((tt)+3<NT){WAIT_BAR(2);} else if((tt)+2<NT){WAIT_BAR(1);} else {WAIT_BAR(0);} }while(0)
; template<int THRL,bool FIXREF,bool HALFK> __device__ __forceinline__ void attn_unit(float mref,long rowbase,int q0,const bf16*Qh,int PQ,const bf16*__restrict__ Kh_,int PK,const bf16*__restrict__ Vh_,int PV,bf16*Oh,int PO,const bf16*Gh,int PG,u32x4(&okeep)[4],int omode,float lam,float oml,const float ...
;     ...
;   for(;t+1<NT;t+=2){
;     STEP(pB0,pB1,pA0,pA1,t,(t+3<NT),(t+1<NT),(t+1<NT));       ENDW(t);   RESC(); ROT();
;     STEP(pA0,pA1,pB0,pB1,t+1,(t+4<NT),(t+2<NT),(t+2<NT));     ENDW(t+1); RESC(); ROT();
	ds_read_b64_tr_b16 v[90:91], v213 offset:40960
	ds_read_b64_tr_b16 v[92:93], v213 offset:41472
	v_add_f32_e32 v66, v114, v115
	v_add_f32_e32 v66, v116, v66
	v_add_f32_e32 v66, v117, v66
	v_add_f32_e32 v66, v118, v66
	v_add_f32_e32 v66, v119, v66
	v_cvt_pk_bf16_f32 v158, v114, v115
	v_cvt_pk_bf16_f32 v159, v116, v117
	s_waitcnt lgkmcnt(5)
	v_mfma_f32_32x32x16_bf16 v[130:145], v[78:81], v[166:169], v[50:65]
	ds_read_b64_tr_b16 v[94:95], v213 offset:45056
	ds_read_b64_tr_b16 v[96:97], v213 offset:45568
	v_add_f32_e32 v66, v120, v66
	v_add_f32_e32 v66, v121, v66
	v_add_f32_e32 v66, v122, v66
	v_add_f32_e32 v114, v123, v66
	s_waitcnt lgkmcnt(6)
	v_mfma_f32_32x32x16_bf16 v[66:81], v[82:85], v[166:169], v[50:65]
	v_cvt_pk_bf16_f32 v160, v118, v119
	v_cvt_pk_bf16_f32 v161, v120, v121
	ds_read_b64_tr_b16 v[82:83], v213 offset:41984
	ds_read_b64_tr_b16 v[84:85], v213 offset:42496
	s_waitcnt lgkmcnt(7)
	v_mfma_f32_32x32x16_bf16 v[130:145], v[86:89], v[162:165], v[130:145]
	v_add_f32_e32 v86, v124, v114
	v_add_f32_e32 v86, v125, v86
	v_add_f32_e32 v86, v126, v86
	v_add_f32_e32 v114, v127, v86
	v_cvt_pk_bf16_f32 v154, v122, v123
	v_cvt_pk_bf16_f32 v155, v124, v125
	ds_read_b64_tr_b16 v[86:87], v213 offset:46080
	ds_read_b64_tr_b16 v[88:89], v213 offset:46592
	s_waitcnt lgkmcnt(8)
	v_mfma_f32_32x32x16_bf16 v[66:81], v[228:231], v[162:165], v[66:81]
	v_add_f32_e32 v114, v128, v114
	v_add_f32_e32 v114, v129, v114
	v_add_f32_e32 v114, v98, v114
	v_add_f32_e32 v118, v99, v114
	v_cvt_pk_bf16_f32 v156, v126, v127
	v_cvt_pk_bf16_f32 v157, v128, v129
	ds_read_b64_tr_b16 v[114:115], v213 offset:43008
	ds_read_b64_tr_b16 v[116:117], v213 offset:43520
	v_add_f32_e32 v118, v100, v118
	v_add_f32_e32 v118, v101, v118
	v_add_f32_e32 v118, v102, v118
	v_add_f32_e32 v118, v103, v118
	v_cvt_pk_bf16_f32 v150, v98, v99
	v_cvt_pk_bf16_f32 v151, v100, v101
	ds_read_b64_tr_b16 v[98:99], v213 offset:47104
	ds_read_b64_tr_b16 v[100:101], v213 offset:47616
	v_add_f32_e32 v118, v104, v118
	v_add_f32_e32 v118, v105, v118
	v_add_f32_e32 v118, v106, v118
	v_add_f32_e32 v118, v107, v118
	v_cvt_pk_bf16_f32 v152, v102, v103
	v_cvt_pk_bf16_f32 v153, v104, v105
	ds_read_b64_tr_b16 v[102:103], v213 offset:44032
	ds_read_b64_tr_b16 v[104:105], v213 offset:44544
	v_add_f32_e32 v118, v108, v118
	v_add_f32_e32 v118, v109, v118
	v_add_f32_e32 v118, v110, v118
	v_add_f32_e32 v118, v111, v118
	v_cvt_pk_bf16_f32 v146, v106, v107
	v_cvt_pk_bf16_f32 v147, v108, v109
	ds_read_b64_tr_b16 v[106:107], v213 offset:48128
	ds_read_b64_tr_b16 v[108:109], v213 offset:48640
	v_add_f32_e32 v118, v112, v118
	v_add_f32_e32 v118, v113, v118
	v_add_f32_e32 v118, 0, v118
	v_cvt_pk_bf16_f32 v148, v110, v111
	v_cvt_pk_bf16_f32 v149, v112, v113
	s_mov_b64 s[50:51], 0x1f8000
	v_lshl_add_u64 v[110:111], v[174:175], 0, s[50:51]
	s_mov_b32 s49, m0
	s_mov_b32 m0, s81
	s_nop 0
	global_load_lds_dwordx4 v[110:111], off
	s_mov_b32 m0, s49
	v_lshl_add_u64 v[110:111], v[172:173], 0, s[6:7]
	s_add_i32 s49, s48, 0x8000
	s_mov_b32 s50, m0
	s_mov_b32 m0, s49
	s_nop 0
	global_load_lds_dwordx4 v[110:111], off
	s_mov_b32 m0, s50
	v_add_f32_e32 v215, v215, v118
	s_waitcnt lgkmcnt(14)
	v_mfma_f32_32x32x16_bf16 v[18:33], v[158:161], v[90:93], v[18:33]
	v_exp_f32_e32 v130, v130
	v_exp_f32_e32 v131, v131
	v_exp_f32_e32 v132, v132
	v_exp_f32_e32 v133, v133
	s_waitcnt lgkmcnt(12)
	v_mfma_f32_32x32x16_bf16 v[34:49], v[158:161], v[94:97], v[34:49]
	v_exp_f32_e32 v134, v134
	v_exp_f32_e32 v135, v135
	v_exp_f32_e32 v136, v136
	v_exp_f32_e32 v137, v137
	ds_read_b128 v[90:93], v214 offset:8192
	ds_read_b128 v[110:113], v214 offset:8704
	s_waitcnt lgkmcnt(12)
	v_mfma_f32_32x32x16_bf16 v[18:33], v[154:157], v[82:85], v[18:33]
	v_exp_f32_e32 v138, v138
	v_exp_f32_e32 v139, v139
	v_exp_f32_e32 v140, v140
	v_exp_f32_e32 v141, v141
	ds_read_b128 v[228:231], v214 offset:10240
	ds_read_b128 v[232:235], v214 offset:10752
	s_waitcnt lgkmcnt(12)
	v_mfma_f32_32x32x16_bf16 v[34:49], v[154:157], v[86:89], v[34:49]
	v_exp_f32_e32 v142, v142
	v_exp_f32_e32 v143, v143
	v_exp_f32_e32 v144, v144
	v_exp_f32_e32 v145, v145
	s_waitcnt lgkmcnt(10)
	v_mfma_f32_32x32x16_bf16 v[18:33], v[150:153], v[114:117], v[18:33]
	v_exp_f32_e32 v66, v66
	v_exp_f32_e32 v67, v67
	v_exp_f32_e32 v68, v68
	v_exp_f32_e32 v69, v69
	s_waitcnt lgkmcnt(8)
	v_mfma_f32_32x32x16_bf16 v[34:49], v[150:153], v[98:101], v[34:49]
	v_exp_f32_e32 v70, v70
	v_exp_f32_e32 v71, v71
	v_exp_f32_e32 v72, v72
	v_exp_f32_e32 v73, v73
	s_waitcnt lgkmcnt(6)
	v_mfma_f32_32x32x16_bf16 v[18:33], v[146:149], v[102:105], v[18:33]
	v_exp_f32_e32 v74, v74
	v_exp_f32_e32 v75, v75
	v_exp_f32_e32 v76, v76
	v_exp_f32_e32 v77, v77
	s_waitcnt lgkmcnt(4)
	v_mfma_f32_32x32x16_bf16 v[34:49], v[146:149], v[106:109], v[34:49]
	v_exp_f32_e32 v78, v78
	v_exp_f32_e32 v79, v79
	v_exp_f32_e32 v80, v80
	v_exp_f32_e32 v81, v81
	s_waitcnt vmcnt(2) lgkmcnt(0)
	s_barrier
;   #define RESC() do{ if(!FIXREF&&resc){ asm volatile("s_waitcnt lgkmcnt(0)":::"memory"); \
;       _Pragma("unroll") for(int d_=0;d_<2;++d_) _Pragma("unroll") for(int r=0;r<16;++r)o[d_][r]*=wsf[crow(r,hi)]; } }while(0)
;   #define ROT() do{sl_prev=sl_cur;sl_cur=sl_next;sl_next=(sl_next==(NSLOT-1)*SLOTB)?0:sl_next+SLOTB;}while(0)
;   #define ENDW(tt) do{ if((tt)+3<NT){WAIT_BAR(2);} else if((tt)+2<NT){WAIT_BAR(1);} else {WAIT_BAR(0);} }while(0)
; template<int THRL,bool FIXREF,bool HALFK> __device__ __forceinline__ void attn_unit(float mref,long rowbase,int q0,const bf16*Qh,int PQ,const bf16*__restrict__ Kh_,int PK,const bf16*__restrict__ Vh_,int PV,bf16*Oh,int PO,const bf16*Gh,int PG,u32x4(&okeep)[4],int omode,float lam,float oml,const float ...
;     ...
;   for(;t+1<NT;t+=2){
;     STEP(pB0,pB1,pA0,pA1,t,(t+3<NT),(t+1<NT),(t+1<NT));       ENDW(t);   RESC(); ROT();
;     STEP(pA0,pA1,pB0,pB1,t+1,(t+4<NT),(t+2<NT),(t+2<NT));     ENDW(t+1); RESC(); ROT();
	ds_read_b64_tr_b16 v[98:99], v213 offset:24576
	ds_read_b64_tr_b16 v[100:101], v213 offset:25088
	v_add_f32_e32 v82, v130, v131
	v_add_f32_e32 v82, v132, v82
	v_add_f32_e32 v82, v133, v82
	v_add_f32_e32 v82, v134, v82
	v_add_f32_e32 v82, v135, v82
	v_cvt_pk_bf16_f32 v158, v130, v131
	v_cvt_pk_bf16_f32 v159, v132, v133
	s_waitcnt lgkmcnt(5)
	v_mfma_f32_32x32x16_bf16 v[114:129], v[90:93], v[166:169], v[50:65]
	ds_read_b64_tr_b16 v[102:103], v213 offset:28672
	ds_read_b64_tr_b16 v[104:105], v213 offset:29184
	v_add_f32_e32 v82, v136, v82
	v_add_f32_e32 v82, v137, v82
	v_add_f32_e32 v82, v138, v82
	v_add_f32_e32 v130, v139, v82
	v_cvt_pk_bf16_f32 v160, v134, v135
	v_cvt_pk_bf16_f32 v161, v136, v137
	s_waitcnt lgkmcnt(6)
	v_mfma_f32_32x32x16_bf16 v[82:97], v[110:113], v[166:169], v[50:65]
	ds_read_b64_tr_b16 v[106:107], v213 offset:25600
	ds_read_b64_tr_b16 v[108:109], v213 offset:26112
	v_add_f32_e32 v110, v140, v130
	v_add_f32_e32 v110, v141, v110
	v_add_f32_e32 v110, v142, v110
	v_add_f32_e32 v130, v143, v110
	v_cvt_pk_bf16_f32 v154, v138, v139
	v_cvt_pk_bf16_f32 v155, v140, v141
	s_waitcnt lgkmcnt(7)
	v_mfma_f32_32x32x16_bf16 v[114:129], v[228:231], v[162:165], v[114:129]
	ds_read_b64_tr_b16 v[110:111], v213 offset:29696
	ds_read_b64_tr_b16 v[112:113], v213 offset:30208
	v_add_f32_e32 v130, v144, v130
	v_add_f32_e32 v130, v145, v130
	v_add_f32_e32 v130, v66, v130
	v_add_f32_e32 v134, v67, v130
	v_cvt_pk_bf16_f32 v156, v142, v143
	v_cvt_pk_bf16_f32 v157, v144, v145
	s_waitcnt lgkmcnt(8)
	v_mfma_f32_32x32x16_bf16 v[82:97], v[232:235], v[162:165], v[82:97]
	ds_read_b64_tr_b16 v[130:131], v213 offset:26624
	ds_read_b64_tr_b16 v[132:133], v213 offset:27136
	v_add_f32_e32 v134, v68, v134
	v_add_f32_e32 v134, v69, v134
	v_add_f32_e32 v134, v70, v134
	v_add_f32_e32 v134, v71, v134
	v_cvt_pk_bf16_f32 v150, v66, v67
	v_cvt_pk_bf16_f32 v151, v68, v69
	ds_read_b64_tr_b16 v[66:67], v213 offset:30720
	ds_read_b64_tr_b16 v[68:69], v213 offset:31232
	v_add_f32_e32 v134, v72, v134
	v_add_f32_e32 v134, v73, v134
	v_add_f32_e32 v134, v74, v134
	v_add_f32_e32 v134, v75, v134
	v_cvt_pk_bf16_f32 v152, v70, v71
	v_cvt_pk_bf16_f32 v153, v72, v73
	ds_read_b64_tr_b16 v[70:71], v213 offset:27648
	ds_read_b64_tr_b16 v[72:73], v213 offset:28160
	v_add_f32_e32 v134, v76, v134
	v_add_f32_e32 v134, v77, v134
	v_add_f32_e32 v134, v78, v134
	v_add_f32_e32 v134, v79, v134
	v_cvt_pk_bf16_f32 v146, v74, v75
	v_cvt_pk_bf16_f32 v147, v76, v77
	ds_read_b64_tr_b16 v[74:75], v213 offset:31744
	ds_read_b64_tr_b16 v[76:77], v213 offset:32256
	v_add_f32_e32 v134, v80, v134
	v_add_f32_e32 v134, v81, v134
	v_add_f32_e32 v134, 0, v134
	v_cvt_pk_bf16_f32 v148, v78, v79
	v_cvt_pk_bf16_f32 v149, v80, v81
	v_lshl_add_u64 v[78:79], v[172:173], 0, s[94:95]
	s_add_i32 s48, s48, 0xa000
	s_mov_b32 s49, m0
	s_mov_b32 m0, s48
	s_nop 0
	global_load_lds_dwordx4 v[78:79], off
	s_mov_b32 m0, s49
	v_add_f32_e32 v174, v215, v134
	s_waitcnt lgkmcnt(14)
	v_mfma_f32_32x32x16_bf16 v[18:33], v[158:161], v[98:101], v[18:33]
	v_exp_f32_e32 v114, v114
	v_exp_f32_e32 v115, v115
	v_exp_f32_e32 v116, v116
	v_exp_f32_e32 v117, v117
	s_waitcnt lgkmcnt(12)
	v_mfma_f32_32x32x16_bf16 v[34:49], v[158:161], v[102:105], v[34:49]
	v_exp_f32_e32 v118, v118
	v_exp_f32_e32 v119, v119
	v_exp_f32_e32 v120, v120
	v_exp_f32_e32 v121, v121
	ds_read_b128 v[78:81], v214 offset:16384
	ds_read_b128 v[134:137], v214 offset:16896
	s_waitcnt lgkmcnt(12)
	v_mfma_f32_32x32x16_bf16 v[18:33], v[154:157], v[106:109], v[18:33]
	v_exp_f32_e32 v122, v122
	v_exp_f32_e32 v123, v123
	v_exp_f32_e32 v124, v124
	v_exp_f32_e32 v125, v125
	ds_read_b128 v[138:141], v214 offset:18432
	ds_read_b128 v[142:145], v214 offset:18944
	s_waitcnt lgkmcnt(12)
	v_mfma_f32_32x32x16_bf16 v[34:49], v[154:157], v[110:113], v[34:49]
	v_exp_f32_e32 v126, v126
	v_exp_f32_e32 v127, v127
	v_exp_f32_e32 v128, v128
	v_exp_f32_e32 v129, v129
	s_waitcnt lgkmcnt(10)
	v_mfma_f32_32x32x16_bf16 v[18:33], v[150:153], v[130:133], v[18:33]
	v_exp_f32_e32 v82, v82
	v_exp_f32_e32 v83, v83
	v_exp_f32_e32 v84, v84
	v_exp_f32_e32 v85, v85
	s_waitcnt lgkmcnt(8)
	v_mfma_f32_32x32x16_bf16 v[34:49], v[150:153], v[66:69], v[34:49]
	v_exp_f32_e32 v86, v86
	v_exp_f32_e32 v87, v87
	v_exp_f32_e32 v88, v88
	v_exp_f32_e32 v89, v89
	s_waitcnt lgkmcnt(6)
	v_mfma_f32_32x32x16_bf16 v[18:33], v[146:149], v[70:73], v[18:33]
	v_exp_f32_e32 v90, v90
	v_exp_f32_e32 v91, v91
	v_exp_f32_e32 v92, v92
	v_exp_f32_e32 v93, v93
	s_waitcnt lgkmcnt(4)
	v_mfma_f32_32x32x16_bf16 v[34:49], v[146:149], v[74:77], v[34:49]
	v_exp_f32_e32 v94, v94
	v_exp_f32_e32 v95, v95
	v_exp_f32_e32 v96, v96
	v_exp_f32_e32 v97, v97
	s_waitcnt vmcnt(1) lgkmcnt(0)
	s_barrier
;   #define RESC() do{ if(!FIXREF&&resc){ asm volatile("s_waitcnt lgkmcnt(0)":::"memory"); \
;       _Pragma("unroll") for(int d_=0;d_<2;++d_) _Pragma("unroll") for(int r=0;r<16;++r)o[d_][r]*=wsf[crow(r,hi)]; } }while(0)
;   #define ROT() do{sl_prev=sl_cur;sl_cur=sl_next;sl_next=(sl_next==(NSLOT-1)*SLOTB)?0:sl_next+SLOTB;}while(0)
;   #define ENDW(tt) do{ if((tt)+3<NT){WAIT_BAR(2);} else if((tt)+2<NT){WAIT_BAR(1);} else {WAIT_BAR(0);} }while(0)
; template<int THRL,bool FIXREF,bool HALFK> __device__ __forceinline__ void attn_unit(float mref,long rowbase,int q0,const bf16*Qh,int PQ,const bf16*__restrict__ Kh_,int PK,const bf16*__restrict__ Vh_,int PV,bf16*Oh,int PO,const bf16*Gh,int PG,u32x4(&okeep)[4],int omode,float lam,float oml,const float ...
;     ...
;   for(;t+1<NT;t+=2){
;     STEP(pB0,pB1,pA0,pA1,t,(t+3<NT),(t+1<NT),(t+1<NT));       ENDW(t);   RESC(); ROT();
;     STEP(pA0,pA1,pB0,pB1,t+1,(t+4<NT),(t+2<NT),(t+2<NT));     ENDW(t+1); RESC(); ROT();
	ds_read_b64_tr_b16 v[130:131], v213 offset:32768
	ds_read_b64_tr_b16 v[132:133], v213 offset:33280
	v_add_f32_e32 v66, v114, v115
	v_add_f32_e32 v66, v116, v66
	v_add_f32_e32 v66, v117, v66
	v_add_f32_e32 v66, v118, v66
	v_add_f32_e32 v66, v119, v66
	v_cvt_pk_bf16_f32 v158, v114, v115
	v_cvt_pk_bf16_f32 v159, v116, v117
	s_waitcnt lgkmcnt(5)
	v_mfma_f32_32x32x16_bf16 v[98:113], v[78:81], v[166:169], v[50:65]
	ds_read_b64_tr_b16 v[114:115], v213 offset:36864
	ds_read_b64_tr_b16 v[116:117], v213 offset:37376
	v_add_f32_e32 v66, v120, v66
	v_add_f32_e32 v66, v121, v66
	v_add_f32_e32 v66, v122, v66
	v_add_f32_e32 v146, v123, v66
	s_waitcnt lgkmcnt(6)
	v_mfma_f32_32x32x16_bf16 v[66:81], v[134:137], v[166:169], v[50:65]
	v_cvt_pk_bf16_f32 v160, v118, v119
	v_cvt_pk_bf16_f32 v161, v120, v121
	ds_read_b64_tr_b16 v[118:119], v213 offset:33792
	ds_read_b64_tr_b16 v[120:121], v213 offset:34304
	v_add_f32_e32 v134, v124, v146
	v_add_f32_e32 v134, v125, v134
	v_add_f32_e32 v134, v126, v134
	s_waitcnt lgkmcnt(7)
	v_mfma_f32_32x32x16_bf16 v[98:113], v[138:141], v[162:165], v[98:113]
	v_add_f32_e32 v138, v127, v134
	v_cvt_pk_bf16_f32 v154, v122, v123
	v_cvt_pk_bf16_f32 v155, v124, v125
	ds_read_b64_tr_b16 v[134:135], v213 offset:37888
	ds_read_b64_tr_b16 v[136:137], v213 offset:38400
	s_waitcnt lgkmcnt(8)
	v_mfma_f32_32x32x16_bf16 v[66:81], v[142:145], v[162:165], v[66:81]
	v_add_f32_e32 v122, v128, v138
	v_add_f32_e32 v122, v129, v122
	v_add_f32_e32 v122, v82, v122
	v_add_f32_e32 v122, v83, v122
	v_cvt_pk_bf16_f32 v156, v126, v127
	v_cvt_pk_bf16_f32 v157, v128, v129
	ds_read_b64_tr_b16 v[124:125], v213 offset:34816
	ds_read_b64_tr_b16 v[126:127], v213 offset:35328
	v_add_f32_e32 v122, v84, v122
	v_add_f32_e32 v122, v85, v122
	v_add_f32_e32 v122, v86, v122
	v_add_f32_e32 v122, v87, v122
	v_cvt_pk_bf16_f32 v150, v82, v83
	v_cvt_pk_bf16_f32 v151, v84, v85
	ds_read_b64_tr_b16 v[82:83], v213 offset:38912
	ds_read_b64_tr_b16 v[84:85], v213 offset:39424
	v_add_f32_e32 v122, v88, v122
	v_add_f32_e32 v122, v89, v122
	v_add_f32_e32 v122, v90, v122
	v_add_f32_e32 v122, v91, v122
	v_cvt_pk_bf16_f32 v152, v86, v87
	v_cvt_pk_bf16_f32 v153, v88, v89
	ds_read_b64_tr_b16 v[86:87], v213 offset:35840
	ds_read_b64_tr_b16 v[88:89], v213 offset:36352
	v_add_f32_e32 v122, v92, v122
	v_add_f32_e32 v122, v93, v122
	v_add_f32_e32 v122, v94, v122
	v_add_f32_e32 v122, v95, v122
	v_cvt_pk_bf16_f32 v146, v90, v91
	v_cvt_pk_bf16_f32 v147, v92, v93
	ds_read_b64_tr_b16 v[90:91], v213 offset:39936
	ds_read_b64_tr_b16 v[92:93], v213 offset:40448
	v_add_f32_e32 v122, v96, v122
	v_add_f32_e32 v122, v97, v122
	v_add_f32_e32 v122, 0, v122
	v_cvt_pk_bf16_f32 v148, v94, v95
	v_cvt_pk_bf16_f32 v149, v96, v97
	v_lshl_add_u64 v[94:95], v[172:173], 0, s[26:27]
	s_mov_b32 s48, m0
	s_mov_b32 m0, s80
	s_nop 0
	global_load_lds_dwordx4 v[94:95], off
	s_mov_b32 m0, s48
	v_add_f32_e32 v122, v174, v122
	s_waitcnt lgkmcnt(14)
	v_mfma_f32_32x32x16_bf16 v[18:33], v[158:161], v[130:133], v[18:33]
	v_exp_f32_e32 v98, v98
	v_exp_f32_e32 v99, v99
	v_exp_f32_e32 v100, v100
	v_exp_f32_e32 v101, v101
	s_waitcnt lgkmcnt(12)
	v_mfma_f32_32x32x16_bf16 v[34:49], v[158:161], v[114:117], v[34:49]
	v_exp_f32_e32 v102, v102
	v_exp_f32_e32 v103, v103
	v_exp_f32_e32 v104, v104
	v_exp_f32_e32 v105, v105
	ds_read_b128 v[128:131], v214
	ds_read_b128 v[138:141], v214 offset:512
	s_waitcnt lgkmcnt(12)
	v_mfma_f32_32x32x16_bf16 v[18:33], v[154:157], v[118:121], v[18:33]
	v_exp_f32_e32 v106, v106
	v_exp_f32_e32 v107, v107
	v_exp_f32_e32 v108, v108
	v_exp_f32_e32 v109, v109
	ds_read_b128 v[142:145], v214 offset:2048
	ds_read_b128 v[172:175], v214 offset:2560
	s_waitcnt lgkmcnt(12)
	v_mfma_f32_32x32x16_bf16 v[34:49], v[154:157], v[134:137], v[34:49]
	v_exp_f32_e32 v110, v110
	v_exp_f32_e32 v111, v111
	v_exp_f32_e32 v112, v112
	v_exp_f32_e32 v113, v113
	s_waitcnt lgkmcnt(10)
	v_mfma_f32_32x32x16_bf16 v[18:33], v[150:153], v[124:127], v[18:33]
	v_exp_f32_e32 v66, v66
	v_exp_f32_e32 v67, v67
	v_exp_f32_e32 v68, v68
	v_exp_f32_e32 v69, v69
	s_waitcnt lgkmcnt(8)
	v_mfma_f32_32x32x16_bf16 v[34:49], v[150:153], v[82:85], v[34:49]
	v_exp_f32_e32 v70, v70
	v_exp_f32_e32 v71, v71
	v_exp_f32_e32 v72, v72
	v_exp_f32_e32 v73, v73
	s_waitcnt lgkmcnt(6)
	v_mfma_f32_32x32x16_bf16 v[18:33], v[146:149], v[86:89], v[18:33]
	v_exp_f32_e32 v74, v74
	v_exp_f32_e32 v75, v75
	v_exp_f32_e32 v76, v76
	v_exp_f32_e32 v77, v77
	s_waitcnt lgkmcnt(4)
	v_mfma_f32_32x32x16_bf16 v[34:49], v[146:149], v[90:93], v[34:49]
	v_exp_f32_e32 v78, v78
	v_exp_f32_e32 v79, v79
	v_exp_f32_e32 v80, v80
	v_exp_f32_e32 v81, v81
	s_waitcnt vmcnt(0) lgkmcnt(0)
	s_barrier
; #define SBAR() __builtin_amdgcn_sched_barrier(0)
;   #define RESC() do{ if(!FIXREF&&resc){ asm volatile("s_waitcnt lgkmcnt(0)":::"memory"); \
;       _Pragma("unroll") for(int d_=0;d_<2;++d_) _Pragma("unroll") for(int r=0;r<16;++r)o[d_][r]*=wsf[crow(r,hi)]; } }while(0)
;   #define PKW(P,B) cvtpk_s(P[B],P[B+1])
; template<int THRL,bool FIXREF,bool HALFK> __device__ __forceinline__ void attn_unit(float mref,long rowbase,int q0,const bf16*Qh,int PQ,const bf16*__restrict__ Kh_,int PK,const bf16*__restrict__ Vh_,int PV,bf16*Oh,int PO,const bf16*Gh,int PG,u32x4(&okeep)[4],int omode,float lam,float oml,const float ...
;     ...
;   STEP(pB0,pB1,pA0,pA1,NT-1,false,false,false); RESC();
;   { float sacc=pB0[0]+pB0[1]; _Pragma("unroll") for(int r=2;r<16;++r)sacc+=pB0[r]; _Pragma("unroll") for(int r=0;r<16;++r)sacc+=pB1[r]; l_reg+=sacc;
;     pw0=(u32x4){PKW(pB0,0),PKW(pB0,2),PKW(pB0,4),PKW(pB0,6)};pw1=(u32x4){PKW(pB0,8),PKW(pB0,10),PKW(pB0,12),PKW(pB0,14)};pw2=(u32x4){PKW(pB1,0),PKW(pB1,2),PKW(pB1,4),PKW(pB1,6)};pw3=(u32x4){PKW(pB1,8),PKW(pB1,10),PKW(pB1,12),PKW(pB1,14)};
;     SBAR(); pv(o,vb0+sl_cur,PAF(0),PAF(1),PAF(2),PAF(3)); }
	ds_read_b64_tr_b16 v[114:115], v213 offset:40960
	ds_read_b64_tr_b16 v[116:117], v213 offset:41472
	v_add_f32_e32 v82, v98, v99
	v_add_f32_e32 v82, v100, v82
	v_add_f32_e32 v82, v101, v82
	v_add_f32_e32 v82, v102, v82
	v_add_f32_e32 v118, v103, v82
	v_cvt_pk_bf16_f32 v158, v98, v99
	v_cvt_pk_bf16_f32 v159, v100, v101
	s_waitcnt lgkmcnt(5)
	v_mfma_f32_32x32x16_bf16 v[82:97], v[128:131], v[166:169], v[50:65]
	ds_read_b64_tr_b16 v[98:99], v213 offset:45056
	ds_read_b64_tr_b16 v[100:101], v213 offset:45568
	v_add_f32_e32 v118, v104, v118
	v_add_f32_e32 v118, v105, v118
	v_add_f32_e32 v118, v106, v118
	v_add_f32_e32 v123, v107, v118
	v_cvt_pk_bf16_f32 v160, v102, v103
	v_cvt_pk_bf16_f32 v161, v104, v105
	s_waitcnt lgkmcnt(6)
	v_mfma_f32_32x32x16_bf16 v[50:65], v[138:141], v[166:169], v[50:65]
	ds_read_b64_tr_b16 v[118:119], v213 offset:41984
	ds_read_b64_tr_b16 v[120:121], v213 offset:42496
	v_add_f32_e32 v102, v108, v123
	v_add_f32_e32 v102, v109, v102
	v_add_f32_e32 v102, v110, v102
	v_add_f32_e32 v123, v111, v102
	v_cvt_pk_bf16_f32 v154, v106, v107
	v_cvt_pk_bf16_f32 v155, v108, v109
	s_waitcnt lgkmcnt(7)
	v_mfma_f32_32x32x16_bf16 v[82:97], v[142:145], v[162:165], v[82:97]
	ds_read_b64_tr_b16 v[102:103], v213 offset:46080
	ds_read_b64_tr_b16 v[104:105], v213 offset:46592
	v_add_f32_e32 v106, v112, v123
	v_add_f32_e32 v106, v113, v106
	v_add_f32_e32 v106, v66, v106
	v_add_f32_e32 v123, v67, v106
	v_cvt_pk_bf16_f32 v156, v110, v111
	v_cvt_pk_bf16_f32 v157, v112, v113
	s_waitcnt lgkmcnt(8)
	v_mfma_f32_32x32x16_bf16 v[50:65], v[172:175], v[162:165], v[50:65]
	ds_read_b64_tr_b16 v[106:107], v213 offset:43008
	ds_read_b64_tr_b16 v[108:109], v213 offset:43520
	v_add_f32_e32 v110, v68, v123
	v_add_f32_e32 v110, v69, v110
	v_add_f32_e32 v110, v70, v110
	v_add_f32_e32 v110, v71, v110
	v_cvt_pk_bf16_f32 v150, v66, v67
	v_cvt_pk_bf16_f32 v151, v68, v69
	ds_read_b64_tr_b16 v[66:67], v213 offset:47104
	ds_read_b64_tr_b16 v[68:69], v213 offset:47616
	v_add_f32_e32 v110, v72, v110
	v_add_f32_e32 v110, v73, v110
	v_add_f32_e32 v110, v74, v110
	v_add_f32_e32 v123, v75, v110
	v_cvt_pk_bf16_f32 v152, v70, v71
	v_cvt_pk_bf16_f32 v153, v72, v73
	ds_read_b64_tr_b16 v[110:111], v213 offset:44032
	ds_read_b64_tr_b16 v[112:113], v213 offset:44544
	v_add_f32_e32 v70, v76, v123
	v_add_f32_e32 v70, v77, v70
	v_add_f32_e32 v70, v78, v70
	v_add_f32_e32 v123, v79, v70
	v_cvt_pk_bf16_f32 v146, v74, v75
	v_cvt_pk_bf16_f32 v147, v76, v77
	ds_read_b64_tr_b16 v[70:71], v213 offset:48128
	ds_read_b64_tr_b16 v[72:73], v213 offset:48640
	v_add_f32_e32 v74, v80, v123
	v_add_f32_e32 v74, v81, v74
	v_add_f32_e32 v74, 0, v74
	v_cvt_pk_bf16_f32 v148, v78, v79
	v_cvt_pk_bf16_f32 v149, v80, v81
	v_exp_f32_e32 v82, v82
	v_exp_f32_e32 v83, v83
	v_exp_f32_e32 v84, v84
	v_exp_f32_e32 v85, v85
	s_nop 0
	v_exp_f32_e32 v86, v86
	v_exp_f32_e32 v87, v87
	v_exp_f32_e32 v88, v88
	v_exp_f32_e32 v89, v89
	s_nop 0
	v_exp_f32_e32 v90, v90
	v_exp_f32_e32 v91, v91
	v_exp_f32_e32 v92, v92
	v_exp_f32_e32 v93, v93
	s_nop 0
	v_exp_f32_e32 v94, v94
	v_exp_f32_e32 v95, v95
	v_exp_f32_e32 v96, v96
	v_exp_f32_e32 v97, v97
	v_exp_f32_e32 v50, v50
	v_exp_f32_e32 v51, v51
	v_exp_f32_e32 v52, v52
	v_exp_f32_e32 v53, v53
	s_nop 0
	v_exp_f32_e32 v54, v54
	v_exp_f32_e32 v55, v55
	v_exp_f32_e32 v56, v56
	v_exp_f32_e32 v57, v57
	s_nop 0
	v_exp_f32_e32 v58, v58
	v_exp_f32_e32 v59, v59
	v_exp_f32_e32 v60, v60
	v_exp_f32_e32 v61, v61
	s_nop 0
	v_exp_f32_e32 v62, v62
	v_exp_f32_e32 v63, v63
	v_exp_f32_e32 v64, v64
	v_exp_f32_e32 v65, v65
	s_waitcnt lgkmcnt(14)
	v_mfma_f32_32x32x16_bf16 v[18:33], v[158:161], v[114:117], v[18:33]
	v_add_f32_e32 v75, v82, v83
	v_add_f32_e32 v75, v84, v75
	v_add_f32_e32 v75, v85, v75
	v_add_f32_e32 v75, v86, v75
	v_add_f32_e32 v75, v87, v75
	v_add_f32_e32 v75, v88, v75
	v_add_f32_e32 v75, v89, v75
	s_waitcnt lgkmcnt(12)
	v_mfma_f32_32x32x16_bf16 v[34:49], v[158:161], v[98:101], v[34:49]
	v_add_f32_e32 v75, v90, v75
	v_add_f32_e32 v75, v91, v75
	v_add_f32_e32 v75, v92, v75
	v_add_f32_e32 v75, v93, v75
	v_add_f32_e32 v75, v94, v75
	v_add_f32_e32 v75, v95, v75
	v_add_f32_e32 v75, v96, v75
	s_waitcnt lgkmcnt(10)
	v_mfma_f32_32x32x16_bf16 v[18:33], v[154:157], v[118:121], v[18:33]
	v_add_f32_e32 v75, v97, v75
	v_add_f32_e32 v75, v50, v75
	v_add_f32_e32 v75, v51, v75
	v_add_f32_e32 v75, v52, v75
	v_add_f32_e32 v75, v53, v75
	v_add_f32_e32 v75, v54, v75
	v_add_f32_e32 v75, v55, v75
	s_waitcnt lgkmcnt(8)
	v_mfma_f32_32x32x16_bf16 v[34:49], v[154:157], v[102:105], v[34:49]
	v_add_f32_e32 v75, v56, v75
	v_add_f32_e32 v75, v57, v75
	v_add_f32_e32 v75, v58, v75
	v_add_f32_e32 v75, v59, v75
	v_add_f32_e32 v75, v60, v75
	v_add_f32_e32 v75, v61, v75
	v_add_f32_e32 v75, v62, v75
	s_waitcnt lgkmcnt(6)
	v_mfma_f32_32x32x16_bf16 v[18:33], v[150:153], v[106:109], v[18:33]
	v_add_f32_e32 v75, v63, v75
	v_add_f32_e32 v75, v64, v75
	v_add_f32_e32 v75, v65, v75
	v_add_f32_e32 v74, v122, v74
	v_add_f32_e32 v74, v74, v75
	v_cvt_pk_bf16_f32 v76, v82, v83
	v_cvt_pk_bf16_f32 v77, v84, v85
	s_waitcnt lgkmcnt(4)
	v_mfma_f32_32x32x16_bf16 v[34:49], v[150:153], v[66:69], v[34:49]
	v_cvt_pk_bf16_f32 v78, v86, v87
	v_cvt_pk_bf16_f32 v79, v88, v89
	v_cvt_pk_bf16_f32 v80, v90, v91
	v_cvt_pk_bf16_f32 v81, v92, v93
	v_cvt_pk_bf16_f32 v82, v94, v95
	v_cvt_pk_bf16_f32 v83, v96, v97
	v_cvt_pk_bf16_f32 v50, v50, v51
	s_waitcnt lgkmcnt(2)
	v_mfma_f32_32x32x16_bf16 v[18:33], v[146:149], v[110:113], v[18:33]
	v_cvt_pk_bf16_f32 v51, v52, v53
	v_cvt_pk_bf16_f32 v52, v54, v55
	v_cvt_pk_bf16_f32 v53, v56, v57
	v_cvt_pk_bf16_f32 v54, v58, v59
	v_cvt_pk_bf16_f32 v55, v60, v61
	v_cvt_pk_bf16_f32 v56, v62, v63
	v_cvt_pk_bf16_f32 v57, v64, v65
	s_waitcnt lgkmcnt(0)
; __device__ __forceinline__ int crow(int r,int hi){return (r&3)+8*(r>>2)+4*hi;}
; #define SBAR() __builtin_amdgcn_sched_barrier(0)
; __device__ __forceinline__ void pv(f32x16*o,int vb,bf16x8 pa0,bf16x8 pa1,bf16x8 pa2,bf16x8 pa3){
;   #pragma unroll
;   for(int d0=0;d0<2;++d0){s16x4 lo[4],hi[4];
;     #pragma unroll
;     for(int ks=0;ks<4;++ks){
;       asm volatile("ds_read_b64_tr_b16 %0,%1 offset:%c2":"=&v"(lo[ks]):"v"(vb),"i"(d0*4096+ks*1024):"memory");
;       asm volatile("ds_read_b64_tr_b16 %0,%1 offset:%c2":"=&v"(hi[ks]):"v"(vb),"i"(d0*4096+ks*1024+512):"memory");}
;     asm volatile("s_waitcnt lgkmcnt(0)":::"memory");SBAR();
;     ...
;     o[d0]=__builtin_amdgcn_mfma_f32_32x32x16_bf16(pa0,PK(0),o[d0],0,0,0);
;     o[d0]=__builtin_amdgcn_mfma_f32_32x32x16_bf16(pa1,PK(1),o[d0],0,0,0);
;     o[d0]=__builtin_amdgcn_mfma_f32_32x32x16_bf16(pa2,PK(2),o[d0],0,0,0);
;     o[d0]=__builtin_amdgcn_mfma_f32_32x32x16_bf16(pa3,PK(3),o[d0],0,0,0);
;     ...
;   }
; template<int THRL,bool FIXREF,bool HALFK> __device__ __forceinline__ void attn_unit(float mref,long rowbase,int q0,const bf16*Qh,int PQ,const bf16*__restrict__ Kh_,int PK,const bf16*__restrict__ Vh_,int PV,bf16*Oh,int PO,const bf16*Gh,int PG,u32x4(&okeep)[4],int omode,float lam,float oml,const float ...
;     ...
;   {auto rr=__builtin_amdgcn_permlane32_swap(__float_as_uint(l_reg),__float_as_uint(l_reg),false,false);l_reg=__uint_as_float(rr[0])+__uint_as_float(rr[1]);}
;   if(hi==0)wsf[32+r32]=l_reg;asm volatile("s_waitcnt lgkmcnt(0)":::"memory");
;   float rli[16];
;   #pragma unroll
;   for(int r=0;r<16;++r)rli[r]=__builtin_amdgcn_rcpf(wsf[32+crow(r,hi)]);
;   bf16*Ow=Oh+(rowbase+q0+wid*QBLK)*PO;
;   { bf16*stg=(bf16*)(shm+LDS_OST)+wid*2048;
;     #pragma unroll
;     for(int r=0;r<16;++r){const int orow=crow(r,hi);
;       #pragma unroll
;       for(int d0=0;d0<2;++d0)stg[orow*64+d0*32+r32]=__float2bfloat16(o[d0][r]*rli[r]);}
;     asm volatile("s_waitcnt lgkmcnt(0)":::"memory");
	v_mfma_f32_32x32x16_bf16 v[34:49], v[146:149], v[70:73], v[34:49]
	ds_read_b64_tr_b16 v[58:59],v0 offset:0
	ds_read_b64_tr_b16 v[60:61],v0 offset:512
	ds_read_b64_tr_b16 v[62:63],v0 offset:1024
	ds_read_b64_tr_b16 v[64:65],v0 offset:1536
	ds_read_b64_tr_b16 v[66:67],v0 offset:2048
	ds_read_b64_tr_b16 v[68:69],v0 offset:2560
	ds_read_b64_tr_b16 v[70:71],v0 offset:3072
	ds_read_b64_tr_b16 v[72:73],v0 offset:3584
	s_waitcnt lgkmcnt(0)
	s_nop 0
	v_mfma_f32_32x32x16_bf16 v[18:33], v[76:79], v[58:61], v[18:33]
	ds_read_b64_tr_b16 v[58:59],v0 offset:4096
	ds_read_b64_tr_b16 v[60:61],v0 offset:4608
	v_mfma_f32_32x32x16_bf16 v[18:33], v[80:83], v[62:65], v[18:33]
	ds_read_b64_tr_b16 v[62:63],v0 offset:5120
	ds_read_b64_tr_b16 v[64:65],v0 offset:5632
	v_mfma_f32_32x32x16_bf16 v[18:33], v[50:53], v[66:69], v[18:33]
	ds_read_b64_tr_b16 v[66:67],v0 offset:6144
	ds_read_b64_tr_b16 v[68:69],v0 offset:6656
	v_mfma_f32_32x32x16_bf16 v[18:33], v[54:57], v[70:73], v[18:33]
	ds_read_b64_tr_b16 v[70:71],v0 offset:7168
	ds_read_b64_tr_b16 v[72:73],v0 offset:7680
	s_waitcnt lgkmcnt(0)
	v_mfma_f32_32x32x16_bf16 v[34:49], v[76:79], v[58:61], v[34:49]
	v_mov_b32_e32 v0, v74
	s_nop 1
	v_permlane32_swap_b32_e32 v74, v0
	v_cmp_gt_u32_e32 vcc, 32, v209
	v_mfma_f32_32x32x16_bf16 v[34:49], v[80:83], v[62:65], v[34:49]
	v_mfma_f32_32x32x16_bf16 v[34:49], v[50:53], v[66:69], v[34:49]
	v_mfma_f32_32x32x16_bf16 v[34:49], v[54:57], v[70:73], v[34:49]
	s_and_saveexec_b64 s[48:49], vcc
	v_lshl_add_u32 v50, v171, 2, s20
	v_add_f32_e32 v0, v74, v0
	ds_write_b32 v50, v0 offset:49280
	s_or_b64 exec, exec, s[48:49]
	s_waitcnt lgkmcnt(0)
	v_lshl_add_u32 v0, v212, 4, s20
	ds_read_b128 v[50:53], v0 offset:49280
	ds_read_b128 v[54:57], v0 offset:49312
	s_lshl_b32 s20, s79, 12
	s_add_i32 s20, s20, 0
	v_lshlrev_b32_e32 v66, 1, v171
	s_waitcnt lgkmcnt(1)
	v_rcp_f32_e32 v58, v50
	v_rcp_f32_e32 v59, v51
	v_rcp_f32_e32 v60, v52
	v_rcp_f32_e32 v61, v53
	s_waitcnt lgkmcnt(0)
	v_rcp_f32_e32 v62, v54
	ds_read_b128 v[50:53], v0 offset:49344
	v_rcp_f32_e32 v63, v55
	v_rcp_f32_e32 v64, v56
	v_rcp_f32_e32 v65, v57
	ds_read_b128 v[54:57], v0 offset:49376
	s_waitcnt lgkmcnt(1)
	v_rcp_f32_e32 v0, v50
	v_rcp_f32_e32 v50, v51
	v_rcp_f32_e32 v51, v52
	v_rcp_f32_e32 v52, v53
	s_waitcnt lgkmcnt(0)
	v_rcp_f32_e32 v53, v54
	v_rcp_f32_e32 v54, v55
	v_rcp_f32_e32 v55, v56
	v_rcp_f32_e32 v56, v57
	v_lshlrev_b32_e32 v57, 9, v212
	v_mul_f32_e32 v18, v18, v58
	v_add3_u32 v57, s20, v57, v66
	v_cvt_pk_bf16_f32 v18, v18, s0
	ds_write_b16 v57, v18 offset:51200
	v_mul_f32_e32 v18, v34, v58
	v_cvt_pk_bf16_f32 v18, v18, s0
	ds_write_b16 v57, v18 offset:51264
	v_mul_f32_e32 v18, v19, v59
	v_cvt_pk_bf16_f32 v18, v18, s0
	ds_write_b16 v57, v18 offset:51328
	v_mul_f32_e32 v18, v35, v59
	v_cvt_pk_bf16_f32 v18, v18, s0
	ds_write_b16 v57, v18 offset:51392
	v_mul_f32_e32 v18, v20, v60
	v_cvt_pk_bf16_f32 v18, v18, s0
	ds_write_b16 v57, v18 offset:51456
	v_mul_f32_e32 v18, v36, v60
	v_cvt_pk_bf16_f32 v18, v18, s0
	ds_write_b16 v57, v18 offset:51520
	v_mul_f32_e32 v18, v21, v61
	v_cvt_pk_bf16_f32 v18, v18, s0
	ds_write_b16 v57, v18 offset:51584
	v_mul_f32_e32 v18, v37, v61
	v_cvt_pk_bf16_f32 v18, v18, s0
	ds_write_b16 v57, v18 offset:51648
	v_mul_f32_e32 v18, v22, v62
	v_cvt_pk_bf16_f32 v18, v18, s0
	ds_write_b16 v57, v18 offset:52224
	v_mul_f32_e32 v18, v38, v62
	v_cvt_pk_bf16_f32 v18, v18, s0
	ds_write_b16 v57, v18 offset:52288
	v_mul_f32_e32 v18, v23, v63
	v_cvt_pk_bf16_f32 v18, v18, s0
	ds_write_b16 v57, v18 offset:52352
	v_mul_f32_e32 v18, v39, v63
	v_cvt_pk_bf16_f32 v18, v18, s0
	ds_write_b16 v57, v18 offset:52416
	v_mul_f32_e32 v18, v24, v64
	v_cvt_pk_bf16_f32 v18, v18, s0
	ds_write_b16 v57, v18 offset:52480
	v_mul_f32_e32 v18, v40, v64
	v_cvt_pk_bf16_f32 v18, v18, s0
	ds_write_b16 v57, v18 offset:52544
	v_mul_f32_e32 v18, v25, v65
	v_cvt_pk_bf16_f32 v18, v18, s0
	ds_write_b16 v57, v18 offset:52608
	v_mul_f32_e32 v18, v41, v65
	v_cvt_pk_bf16_f32 v18, v18, s0
	ds_write_b16 v57, v18 offset:52672
	v_mul_f32_e32 v18, v26, v0
	v_mul_f32_e32 v0, v42, v0
	v_cvt_pk_bf16_f32 v0, v0, s0
	ds_write_b16 v57, v0 offset:53312
	v_mul_f32_e32 v0, v27, v50
	v_cvt_pk_bf16_f32 v0, v0, s0
	ds_write_b16 v57, v0 offset:53376
	v_mul_f32_e32 v0, v43, v50
	v_cvt_pk_bf16_f32 v0, v0, s0
	ds_write_b16 v57, v0 offset:53440
	v_mul_f32_e32 v0, v28, v51
	v_cvt_pk_bf16_f32 v0, v0, s0
	ds_write_b16 v57, v0 offset:53504
	v_mul_f32_e32 v0, v44, v51
	v_cvt_pk_bf16_f32 v0, v0, s0
	ds_write_b16 v57, v0 offset:53568
	v_mul_f32_e32 v0, v29, v52
	v_cvt_pk_bf16_f32 v0, v0, s0
	ds_write_b16 v57, v0 offset:53632
	v_mul_f32_e32 v0, v45, v52
	v_cvt_pk_bf16_f32 v0, v0, s0
	ds_write_b16 v57, v0 offset:53696
	v_mul_f32_e32 v0, v30, v53
	v_cvt_pk_bf16_f32 v0, v0, s0
	ds_write_b16 v57, v0 offset:54272
	v_mul_f32_e32 v0, v46, v53
	v_cvt_pk_bf16_f32 v0, v0, s0
	ds_write_b16 v57, v0 offset:54336
	v_mul_f32_e32 v0, v31, v54
	v_cvt_pk_bf16_f32 v0, v0, s0
	ds_write_b16 v57, v0 offset:54400
	v_mul_f32_e32 v0, v47, v54
	v_cvt_pk_bf16_f32 v0, v0, s0
	ds_write_b16 v57, v0 offset:54464
	v_mul_f32_e32 v0, v32, v55
	v_cvt_pk_bf16_f32 v0, v0, s0
	ds_write_b16 v57, v0 offset:54528
	v_mul_f32_e32 v0, v48, v55
	v_cvt_pk_bf16_f32 v0, v0, s0
	ds_write_b16 v57, v0 offset:54592
	v_mul_f32_e32 v0, v33, v56
	v_cvt_pk_bf16_f32 v0, v0, s0
	ds_write_b16 v57, v0 offset:54656
	v_mul_f32_e32 v0, v49, v56
	v_cvt_pk_bf16_f32 v18, v18, s0
	v_cvt_pk_bf16_f32 v0, v0, s0
	ds_write_b16 v57, v18 offset:53248
	ds_write_b16 v57, v0 offset:54720
	s_lshl_b64 s[46:47], s[46:47], 11
	s_waitcnt lgkmcnt(0)
	s_add_u32 s46, s69, s46
	s_addc_u32 s47, s70, s47
	s_mov_b64 s[48:49], -1
	s_and_b64 vcc, exec, s[42:43]
	s_cbranch_vccz .LBB0_470
; __device__ __forceinline__ unsigned cvtpk_s(float lo,float hi){f32x2_t v={lo,hi};bf16x2_t b=__builtin_convertvector(v,bf16x2_t);return __builtin_bit_cast(unsigned,b);}
; template<int THRL,bool FIXREF,bool HALFK> __device__ __forceinline__ void attn_unit(float mref,long rowbase,int q0,const bf16*Qh,int PQ,const bf16*__restrict__ Kh_,int PK,const bf16*__restrict__ Vh_,int PV,bf16*Oh,int PO,const bf16*Gh,int PG,u32x4(&okeep)[4],int omode,float lam,float oml,const float ...
;     ...
;     else if(Gh){
;       u32x4 gv[4]; const char*gst=shm+LDS_GST+wid*4096+lane*16;
;       #pragma unroll
;       for(int i=0;i<4;++i) gv[i]=*(const u32x4*)(gst+i*1024);
;       #pragma unroll
;       for(int i=0;i<4;++i){const int row=i*8+(lane>>3),ch=lane&7; u32x4 v=*(const u32x4*)(stg+row*64+ch*8);
;         #pragma unroll
;         for(int k=0;k<4;++k){ const float g0=__uint_as_float(gv[i][k]<<16),g1=__uint_as_float(gv[i][k]&0xffff0000u),o0=__uint_as_float(v[k]<<16),o1=__uint_as_float(v[k]&0xffff0000u);
;           v[k]=cvtpk_s(o0*g0*__builtin_amdgcn_rcpf(1.f+__builtin_amdgcn_exp2f(-1.4426950408889634f*g0)),o1*g1*__builtin_amdgcn_rcpf(1.f+__builtin_amdgcn_exp2f(-1.4426950408889634f*g1))); }
;         ATTN_STORE16(Ow+(long)row*PO+ch*8,v);} }
	s_mov_b64 s[42:43], -1
	s_and_b64 vcc, exec, s[40:41]
	s_cbranch_vccz .LBB0_467
	v_lshl_add_u32 v0, v209, 4, s20
	v_add_u32_e32 v0, 0x14800, v0
	ds_read_b128 v[30:33], v0
	ds_read_b128 v[26:29], v0 offset:1024
	ds_read_b128 v[22:25], v0 offset:2048
	ds_read_b128 v[18:21], v0 offset:3072
	v_lshlrev_b32_e32 v0, 1, v211
	v_and_b32_e32 v0, 0x70, v0
	v_add_u32_e32 v36, s20, v0
	v_lshl_add_u64 v[34:35], s[46:47], 0, v[0:1]
	v_lshl_add_u32 v0, v208, 7, v36
	s_waitcnt lgkmcnt(3)
	v_lshlrev_b32_e32 v44, 16, v30
	ds_read_b128 v[38:41], v0 offset:51200
	v_mul_f32_e32 v0, 0xbfb8aa3b, v44
	v_exp_f32_e32 v0, v0
	v_and_b32_e32 v43, 0xffff0000, v30
	s_mov_b64 s[42:43], 0
	s_waitcnt lgkmcnt(0)
	v_lshlrev_b32_e32 v42, 16, v38
	v_add_f32_e32 v0, 1.0, v0
	v_rcp_f32_e32 v46, v0
	v_mul_f32_e32 v0, 0xbfb8aa3b, v43
	v_exp_f32_e32 v0, v0
	v_and_b32_e32 v45, 0xffff0000, v38
	v_lshlrev_b32_e32 v38, 16, v31
	v_pk_mul_f32 v[44:45], v[42:43], v[44:45]
	v_add_f32_e32 v0, 1.0, v0
	v_rcp_f32_e32 v47, v0
	v_mul_f32_e32 v0, 0xbfb8aa3b, v38
	v_exp_f32_e32 v0, v0
	v_pk_mul_f32 v[42:43], v[46:47], v[44:45]
	s_nop 0
	v_cvt_pk_bf16_f32 v30, v42, v43
	v_and_b32_e32 v43, 0xffff0000, v31
	v_add_f32_e32 v0, 1.0, v0
	v_rcp_f32_e32 v44, v0
	v_mul_f32_e32 v0, 0xbfb8aa3b, v43
	v_exp_f32_e32 v0, v0
	v_lshlrev_b32_e32 v42, 16, v39
	v_and_b32_e32 v39, 0xffff0000, v39
	v_pk_mul_f32 v[38:39], v[42:43], v[38:39]
	v_add_f32_e32 v0, 1.0, v0
	v_lshlrev_b32_e32 v42, 16, v32
	v_rcp_f32_e32 v45, v0
	v_mul_f32_e32 v0, 0xbfb8aa3b, v42
	v_exp_f32_e32 v0, v0
	v_and_b32_e32 v43, 0xffff0000, v40
	v_pk_mul_f32 v[38:39], v[44:45], v[38:39]
	v_add_f32_e32 v0, 1.0, v0
	v_cvt_pk_bf16_f32 v31, v38, v39
	v_and_b32_e32 v39, 0xffff0000, v32
	v_rcp_f32_e32 v44, v0
	v_mul_f32_e32 v0, 0xbfb8aa3b, v39
	v_exp_f32_e32 v0, v0
	v_lshlrev_b32_e32 v38, 16, v40
	v_lshlrev_b32_e32 v40, 16, v33
	v_pk_mul_f32 v[42:43], v[38:39], v[42:43]
	v_add_f32_e32 v0, 1.0, v0
	v_rcp_f32_e32 v45, v0
	v_mul_f32_e32 v0, 0xbfb8aa3b, v40
	v_exp_f32_e32 v0, v0
	v_pk_mul_f32 v[38:39], v[44:45], v[42:43]
	s_nop 0
	v_cvt_pk_bf16_f32 v32, v38, v39
	v_and_b32_e32 v39, 0xffff0000, v33
	v_add_f32_e32 v0, 1.0, v0
	v_rcp_f32_e32 v42, v0
	v_mul_f32_e32 v0, 0xbfb8aa3b, v39
	v_exp_f32_e32 v0, v0
	v_lshlrev_b32_e32 v38, 16, v41
	v_and_b32_e32 v41, 0xffff0000, v41
	v_pk_mul_f32 v[40:41], v[38:39], v[40:41]
	v_add_f32_e32 v0, 1.0, v0
	v_rcp_f32_e32 v43, v0
	v_lshlrev_b32_e32 v0, 11, v208
	v_pk_mul_f32 v[38:39], v[42:43], v[40:41]
	s_nop 0
	v_cvt_pk_bf16_f32 v33, v38, v39
	v_lshl_add_u64 v[38:39], v[34:35], 0, v[0:1]
	v_lshlrev_b32_e32 v40, 16, v26
	global_store_dwordx4 v[38:39], v[30:33], off
	v_and_b32_e32 v39, 0xffff0000, v26
	v_mul_f32_e32 v26, 0xbfb8aa3b, v40
	v_exp_f32_e32 v26, v26
	v_or_b32_e32 v0, 8, v208
	v_lshl_add_u32 v30, v0, 7, v36
	ds_read_b128 v[30:33], v30 offset:51200
	v_add_f32_e32 v26, 1.0, v26
	v_rcp_f32_e32 v42, v26
	v_mul_f32_e32 v26, 0xbfb8aa3b, v39
	v_exp_f32_e32 v26, v26
	s_waitcnt lgkmcnt(0)
	v_lshlrev_b32_e32 v38, 16, v30
	v_and_b32_e32 v41, 0xffff0000, v30
	v_pk_mul_f32 v[40:41], v[38:39], v[40:41]
	v_add_f32_e32 v26, 1.0, v26
	v_rcp_f32_e32 v43, v26
	v_lshlrev_b32_e32 v30, 16, v27
	v_lshlrev_b32_e32 v0, 11, v0
	v_pk_mul_f32 v[38:39], v[42:43], v[40:41]
	s_nop 0
	v_cvt_pk_bf16_f32 v26, v38, v39
	v_and_b32_e32 v39, 0xffff0000, v27
	v_mul_f32_e32 v27, 0xbfb8aa3b, v30
	v_exp_f32_e32 v27, v27
	v_lshlrev_b32_e32 v38, 16, v31
	v_and_b32_e32 v31, 0xffff0000, v31
	v_pk_mul_f32 v[30:31], v[38:39], v[30:31]
	v_add_f32_e32 v27, 1.0, v27
	v_rcp_f32_e32 v40, v27
	v_mul_f32_e32 v27, 0xbfb8aa3b, v39
	v_exp_f32_e32 v27, v27
	v_lshlrev_b32_e32 v38, 16, v28
	v_and_b32_e32 v39, 0xffff0000, v32
	v_add_f32_e32 v27, 1.0, v27
	v_rcp_f32_e32 v41, v27
	s_nop 0
	v_pk_mul_f32 v[30:31], v[40:41], v[30:31]
	s_nop 0
	v_cvt_pk_bf16_f32 v27, v30, v31
	v_and_b32_e32 v31, 0xffff0000, v28
	v_mul_f32_e32 v28, 0xbfb8aa3b, v38
	v_exp_f32_e32 v28, v28
	v_lshlrev_b32_e32 v30, 16, v32
	v_pk_mul_f32 v[38:39], v[30:31], v[38:39]
	v_lshlrev_b32_e32 v32, 16, v29
	v_add_f32_e32 v28, 1.0, v28
	v_rcp_f32_e32 v40, v28
	v_mul_f32_e32 v28, 0xbfb8aa3b, v31
	v_exp_f32_e32 v28, v28
	s_nop 0
	v_add_f32_e32 v28, 1.0, v28
	v_rcp_f32_e32 v41, v28
	s_nop 0
	v_pk_mul_f32 v[30:31], v[40:41], v[38:39]
	s_nop 0
	v_cvt_pk_bf16_f32 v28, v30, v31
	v_and_b32_e32 v31, 0xffff0000, v29
	v_mul_f32_e32 v29, 0xbfb8aa3b, v32
	v_exp_f32_e32 v29, v29
	v_lshlrev_b32_e32 v30, 16, v33
	v_and_b32_e32 v33, 0xffff0000, v33
	v_pk_mul_f32 v[32:33], v[30:31], v[32:33]
	v_add_f32_e32 v29, 1.0, v29
	v_rcp_f32_e32 v38, v29
	v_mul_f32_e32 v29, 0xbfb8aa3b, v31
	v_exp_f32_e32 v29, v29
	s_nop 0
	v_add_f32_e32 v29, 1.0, v29
	v_rcp_f32_e32 v39, v29
	s_nop 0
	v_pk_mul_f32 v[30:31], v[38:39], v[32:33]
	s_nop 0
	v_cvt_pk_bf16_f32 v29, v30, v31
	v_lshl_add_u64 v[30:31], v[34:35], 0, v[0:1]
	v_lshlrev_b32_e32 v32, 16, v22
	global_store_dwordx4 v[30:31], v[26:29], off
	v_and_b32_e32 v31, 0xffff0000, v22
	v_mul_f32_e32 v22, 0xbfb8aa3b, v32
	v_exp_f32_e32 v22, v22
	v_or_b32_e32 v0, 16, v208
	v_lshl_add_u32 v26, v0, 7, v36
	ds_read_b128 v[26:29], v26 offset:51200
	v_add_f32_e32 v22, 1.0, v22
	v_rcp_f32_e32 v38, v22
	v_mul_f32_e32 v22, 0xbfb8aa3b, v31
	v_exp_f32_e32 v22, v22
	s_waitcnt lgkmcnt(0)
; __device__ __forceinline__ unsigned cvtpk_s(float lo,float hi){f32x2_t v={lo,hi};bf16x2_t b=__builtin_convertvector(v,bf16x2_t);return __builtin_bit_cast(unsigned,b);}
; template<int THRL,bool FIXREF,bool HALFK> __device__ __forceinline__ void attn_unit(float mref,long rowbase,int q0,const bf16*Qh,int PQ,const bf16*__restrict__ Kh_,int PK,const bf16*__restrict__ Vh_,int PV,bf16*Oh,int PO,const bf16*Gh,int PG,u32x4(&okeep)[4],int omode,float lam,float oml,const float ...
;     ...
;     else if(Gh){
;       u32x4 gv[4]; const char*gst=shm+LDS_GST+wid*4096+lane*16;
;       #pragma unroll
;       for(int i=0;i<4;++i) gv[i]=*(const u32x4*)(gst+i*1024);
;       #pragma unroll
;       for(int i=0;i<4;++i){const int row=i*8+(lane>>3),ch=lane&7; u32x4 v=*(const u32x4*)(stg+row*64+ch*8);
;         #pragma unroll
;         for(int k=0;k<4;++k){ const float g0=__uint_as_float(gv[i][k]<<16),g1=__uint_as_float(gv[i][k]&0xffff0000u),o0=__uint_as_float(v[k]<<16),o1=__uint_as_float(v[k]&0xffff0000u);
;           v[k]=cvtpk_s(o0*g0*__builtin_amdgcn_rcpf(1.f+__builtin_amdgcn_exp2f(-1.4426950408889634f*g0)),o1*g1*__builtin_amdgcn_rcpf(1.f+__builtin_amdgcn_exp2f(-1.4426950408889634f*g1))); }
;         ATTN_STORE16(Ow+(long)row*PO+ch*8,v);} }
	v_lshlrev_b32_e32 v30, 16, v26
	v_and_b32_e32 v33, 0xffff0000, v26
	v_pk_mul_f32 v[32:33], v[30:31], v[32:33]
	v_add_f32_e32 v22, 1.0, v22
	v_rcp_f32_e32 v39, v22
	v_lshlrev_b32_e32 v26, 16, v23
	v_lshlrev_b32_e32 v0, 11, v0
	v_pk_mul_f32 v[30:31], v[38:39], v[32:33]
	s_nop 0
	v_cvt_pk_bf16_f32 v22, v30, v31
	v_and_b32_e32 v31, 0xffff0000, v23
	v_mul_f32_e32 v23, 0xbfb8aa3b, v26
	v_exp_f32_e32 v23, v23
	v_lshlrev_b32_e32 v30, 16, v27
	v_and_b32_e32 v27, 0xffff0000, v27
	v_pk_mul_f32 v[26:27], v[30:31], v[26:27]
	v_add_f32_e32 v23, 1.0, v23
	v_rcp_f32_e32 v32, v23
	v_mul_f32_e32 v23, 0xbfb8aa3b, v31
	v_exp_f32_e32 v23, v23
	v_lshlrev_b32_e32 v30, 16, v24
	v_and_b32_e32 v31, 0xffff0000, v28
	v_add_f32_e32 v23, 1.0, v23
	v_rcp_f32_e32 v33, v23
	s_nop 0
	v_pk_mul_f32 v[26:27], v[32:33], v[26:27]
	s_nop 0
	v_cvt_pk_bf16_f32 v23, v26, v27
	v_and_b32_e32 v27, 0xffff0000, v24
	v_mul_f32_e32 v24, 0xbfb8aa3b, v30
	v_exp_f32_e32 v24, v24
	v_lshlrev_b32_e32 v26, 16, v28
	v_pk_mul_f32 v[30:31], v[26:27], v[30:31]
	v_lshlrev_b32_e32 v28, 16, v25
	v_add_f32_e32 v24, 1.0, v24
	v_rcp_f32_e32 v32, v24
	v_mul_f32_e32 v24, 0xbfb8aa3b, v27
	v_exp_f32_e32 v24, v24
	s_nop 0
	v_add_f32_e32 v24, 1.0, v24
	v_rcp_f32_e32 v33, v24
	s_nop 0
	v_pk_mul_f32 v[26:27], v[32:33], v[30:31]
	s_nop 0
	v_cvt_pk_bf16_f32 v24, v26, v27
	v_and_b32_e32 v27, 0xffff0000, v25
	v_mul_f32_e32 v25, 0xbfb8aa3b, v28
	v_exp_f32_e32 v25, v25
	v_lshlrev_b32_e32 v26, 16, v29
	v_and_b32_e32 v29, 0xffff0000, v29
	v_pk_mul_f32 v[28:29], v[26:27], v[28:29]
	v_add_f32_e32 v25, 1.0, v25
	v_rcp_f32_e32 v30, v25
	v_mul_f32_e32 v25, 0xbfb8aa3b, v27
	v_exp_f32_e32 v25, v25
	s_nop 0
	v_add_f32_e32 v25, 1.0, v25
	v_rcp_f32_e32 v31, v25
	s_nop 0
	v_pk_mul_f32 v[26:27], v[30:31], v[28:29]
	s_nop 0
	v_cvt_pk_bf16_f32 v25, v26, v27
	v_lshl_add_u64 v[26:27], v[34:35], 0, v[0:1]
	v_lshlrev_b32_e32 v28, 16, v18
	global_store_dwordx4 v[26:27], v[22:25], off
	v_and_b32_e32 v27, 0xffff0000, v18
	v_mul_f32_e32 v18, 0xbfb8aa3b, v28
	v_exp_f32_e32 v18, v18
	v_or_b32_e32 v0, 24, v208
	v_lshl_add_u32 v22, v0, 7, v36
	ds_read_b128 v[22:25], v22 offset:51200
	v_add_f32_e32 v18, 1.0, v18
	v_rcp_f32_e32 v30, v18
	v_mul_f32_e32 v18, 0xbfb8aa3b, v27
	v_exp_f32_e32 v18, v18
	s_waitcnt lgkmcnt(0)
	v_lshlrev_b32_e32 v26, 16, v22
	v_and_b32_e32 v29, 0xffff0000, v22
	v_pk_mul_f32 v[28:29], v[26:27], v[28:29]
	v_add_f32_e32 v18, 1.0, v18
	v_rcp_f32_e32 v31, v18
	v_lshlrev_b32_e32 v22, 16, v19
	v_lshlrev_b32_e32 v0, 11, v0
	v_pk_mul_f32 v[26:27], v[30:31], v[28:29]
	s_nop 0
	v_cvt_pk_bf16_f32 v18, v26, v27
	v_and_b32_e32 v27, 0xffff0000, v19
	v_mul_f32_e32 v19, 0xbfb8aa3b, v22
	v_exp_f32_e32 v19, v19
	v_lshlrev_b32_e32 v26, 16, v23
	v_and_b32_e32 v23, 0xffff0000, v23
	v_pk_mul_f32 v[22:23], v[26:27], v[22:23]
	v_add_f32_e32 v19, 1.0, v19
	v_rcp_f32_e32 v28, v19
	v_mul_f32_e32 v19, 0xbfb8aa3b, v27
	v_exp_f32_e32 v19, v19
	v_lshlrev_b32_e32 v26, 16, v20
	v_and_b32_e32 v27, 0xffff0000, v24
	v_add_f32_e32 v19, 1.0, v19
	v_rcp_f32_e32 v29, v19
	s_nop 0
	v_pk_mul_f32 v[22:23], v[28:29], v[22:23]
	s_nop 0
	v_cvt_pk_bf16_f32 v19, v22, v23
	v_and_b32_e32 v23, 0xffff0000, v20
	v_mul_f32_e32 v20, 0xbfb8aa3b, v26
	v_exp_f32_e32 v20, v20
	v_lshlrev_b32_e32 v22, 16, v24
	v_pk_mul_f32 v[26:27], v[22:23], v[26:27]
	v_lshlrev_b32_e32 v24, 16, v21
	v_add_f32_e32 v20, 1.0, v20
	v_rcp_f32_e32 v28, v20
	v_mul_f32_e32 v20, 0xbfb8aa3b, v23
	v_exp_f32_e32 v20, v20
	s_nop 0
	v_add_f32_e32 v20, 1.0, v20
	v_rcp_f32_e32 v29, v20
	s_nop 0
	v_pk_mul_f32 v[22:23], v[28:29], v[26:27]
	s_nop 0
	v_cvt_pk_bf16_f32 v20, v22, v23
	v_and_b32_e32 v23, 0xffff0000, v21
	v_mul_f32_e32 v21, 0xbfb8aa3b, v24
	v_exp_f32_e32 v21, v21
	v_lshlrev_b32_e32 v22, 16, v25
	v_and_b32_e32 v25, 0xffff0000, v25
	v_pk_mul_f32 v[24:25], v[22:23], v[24:25]
	v_add_f32_e32 v21, 1.0, v21
	v_rcp_f32_e32 v26, v21
	v_mul_f32_e32 v21, 0xbfb8aa3b, v23
	v_exp_f32_e32 v21, v21
	s_nop 0
	v_add_f32_e32 v21, 1.0, v21
	v_rcp_f32_e32 v27, v21
	s_nop 0
	v_pk_mul_f32 v[22:23], v[26:27], v[24:25]
	s_nop 0
	v_cvt_pk_bf16_f32 v21, v22, v23
	v_lshl_add_u64 v[22:23], v[34:35], 0, v[0:1]
	global_store_dwordx4 v[22:23], v[18:21], off
